# MLA loop: second tile of each barrier interval issues its LDS store / reload pieces three MFMA slots earlier (slots 11-13)
# speedup vs baseline: 1.0061x; 1.0017x over previous
; #define SB() __builtin_amdgcn_sched_barrier(0)
; template <int VAR>
; __device__ __forceinline__ void attn_phase(LAS unsigned char* lds, const AttnP P, int vcu, int G, int wave_s) {
;     ...
;                 if (ND0 == 6) {
;                     KR1(0); KR1(1); KR1(2); KR1(3); SB();
;                     QK1(0, negm); EX2(pc0, 0, w0.x); KR1(4); SB();
;                     QK1(1, negm); EX2(pc0, 2, w0.y); KR1(5); SB();
;                     QK1(2, pn0); EX2(pc0, 4, w0.z); KR1(6); SB();
;                     QK1(3, pn1); EX2(pc0, 6, w0.w); KR1(7); SB();
;                     QK1(4, pn0); EX2(pc0, 8, w1.x); KR1(8); SB();
;                     QK1(5, pn1); EX2(pc0, 10, w1.y); KR1(9); SB();
;                     QK1(6, pn0); EX2(pc0, 12, w1.z); KR1(10); SB();
;                     QK1(7, pn1); EX2(pc0, 14, w1.w); KR1(11); SB();
;                     QK1(8, pn0); EX2(pc1, 0, w2.x); VR1(0); SB();
;                     QK1(9, pn1); EX2(pc1, 2, w2.y); VR1(1); SB();
;                     QK1(10, pn0); EX2(pc1, 4, w2.z); VR1(2); SB();
;                     QK1(11, pn1); EX2(pc1, 6, w2.w); VR1(3); SB();
;                 } else {
;                     KR1(0); KR1(1); KR1(2); KR1(3); SB();
;                     QK1(0, negm); EX2(pc0, 0, w0.x); EX2(pc0, 2, w0.y); KR1(4); SB();
;                     QK1(1, negm); EX2(pc0, 4, w0.z); EX2(pc0, 6, w0.w); KR1(5); SB();
;                     QK1(2, pn0); EX2(pc0, 8, w1.x); EX2(pc0, 10, w1.y); KR1(6); SB();
;                     QK1(3, pn1); EX2(pc0, 12, w1.z); EX2(pc0, 14, w1.w); KR1(7); SB();
;                     QK1(4, pn0); EX2(pc1, 0, w2.x); VR1(0); SB();
;                     QK1(5, pn1); EX2(pc1, 2, w2.y); VR1(1); SB();
;                     QK1(6, pn0); EX2(pc1, 4, w2.z); VR1(2); SB();
;                     QK1(7, pn1); EX2(pc1, 6, w2.w); VR1(3); SB();
;                 }
;                 PV1(0, w0); EX2(pc1, 8, w3.x); VR1(4); SB();
;                 PV1(1, w0); EX2(pc1, 10, w3.y); VR1(5); SB();
;                 PV1(2, w1); EX2(pc1, 12, w3.z); VR1(6); SB();
;                 PV1(3, w1); EX2(pc1, 14, w3.w); VR1(7); SB();
;                 lrun += sacc;
;                 PV1(4, w2); MASK_TILE(pn0, pn1, t + 1); SB();
;                 PV1(5, w2); SB();
;                 PV1(6, w3); SB();
;                 PV1(7, w3); rmn = rowmax32(pn0, pn1); if (!USE_NEGM) rmn -= mref; SB();
.Lmla_p1_go:
	v_exp_f32_e32 v222, v82
	v_exp_f32_e32 v223, v83
	v_add_f32_e32 v164, 0, v222
	v_cvt_pk_bf16_f32 v206, v222, v223
	v_add_f32_e32 v164, v223, v164
	v_exp_f32_e32 v224, v84
	v_exp_f32_e32 v225, v85
	v_add_f32_e32 v164, v224, v164
	v_cvt_pk_bf16_f32 v207, v224, v225
	v_add_f32_e32 v164, v225, v164
	s_waitcnt lgkmcnt(4)
	v_mfma_f32_32x32x16_bf16 v[34:49], v[182:185], v[114:117], v[66:81]
	ds_read_b128 v[198:201], v174 offset:45120
	v_exp_f32_e32 v222, v86
	v_exp_f32_e32 v223, v87
	v_add_f32_e32 v164, v222, v164
	v_cvt_pk_bf16_f32 v208, v222, v223
	v_add_f32_e32 v164, v223, v164
	s_waitcnt lgkmcnt(4)
	v_mfma_f32_32x32x16_bf16 v[50:65], v[186:189], v[114:117], v[66:81]
	ds_read_b128 v[182:185], v174 offset:51776
	v_exp_f32_e32 v224, v88
	v_exp_f32_e32 v225, v89
	v_add_f32_e32 v164, v224, v164
	v_cvt_pk_bf16_f32 v209, v224, v225
	v_add_f32_e32 v164, v225, v164
	s_waitcnt lgkmcnt(3)
	v_mfma_f32_32x32x16_bf16 v[34:49], v[190:193], v[118:121], v[34:49]
	ds_read_b128 v[186:189], v174 offset:45152
	v_exp_f32_e32 v222, v90
	v_exp_f32_e32 v223, v91
	v_add_f32_e32 v164, v222, v164
	v_cvt_pk_bf16_f32 v210, v222, v223
	v_add_f32_e32 v164, v223, v164
	s_waitcnt lgkmcnt(3)
	v_mfma_f32_32x32x16_bf16 v[50:65], v[194:197], v[118:121], v[50:65]
	ds_read_b128 v[190:193], v174 offset:51808
	v_exp_f32_e32 v224, v92
	v_exp_f32_e32 v225, v93
	v_add_f32_e32 v164, v224, v164
	v_cvt_pk_bf16_f32 v211, v224, v225
	v_add_f32_e32 v164, v225, v164
	s_waitcnt lgkmcnt(3)
	v_mfma_f32_32x32x16_bf16 v[34:49], v[198:201], v[122:125], v[34:49]
	ds_read_b128 v[194:197], v174 offset:45184
	v_exp_f32_e32 v222, v94
	v_exp_f32_e32 v223, v95
	v_add_f32_e32 v164, v222, v164
	v_cvt_pk_bf16_f32 v212, v222, v223
	v_add_f32_e32 v164, v223, v164
	s_waitcnt lgkmcnt(3)
	v_mfma_f32_32x32x16_bf16 v[50:65], v[182:185], v[122:125], v[50:65]
	ds_read_b128 v[198:201], v174 offset:51840
	v_exp_f32_e32 v224, v96
	v_exp_f32_e32 v225, v97
	v_add_f32_e32 v164, v224, v164
	v_cvt_pk_bf16_f32 v213, v224, v225
	v_add_f32_e32 v164, v225, v164
	s_waitcnt lgkmcnt(3)
	v_mfma_f32_32x32x16_bf16 v[34:49], v[186:189], v[126:129], v[34:49]
	ds_read_b128 v[182:185], v174 offset:45216
	v_exp_f32_e32 v222, v98
	v_exp_f32_e32 v223, v99
	v_add_f32_e32 v164, v222, v164
	v_cvt_pk_bf16_f32 v214, v222, v223
	v_add_f32_e32 v164, v223, v164
	s_waitcnt lgkmcnt(3)
	v_mfma_f32_32x32x16_bf16 v[50:65], v[190:193], v[126:129], v[50:65]
	ds_read_b128 v[186:189], v174 offset:51872
	v_exp_f32_e32 v224, v100
	v_exp_f32_e32 v225, v101
	v_add_f32_e32 v164, v224, v164
	v_cvt_pk_bf16_f32 v215, v224, v225
	v_add_f32_e32 v164, v225, v164
	s_waitcnt lgkmcnt(3)
	v_mfma_f32_32x32x16_bf16 v[34:49], v[194:197], v[130:133], v[34:49]
	ds_read_b128 v[190:193], v228 offset:35840
	v_exp_f32_e32 v222, v102
	v_exp_f32_e32 v223, v103
	v_add_f32_e32 v164, v222, v164
	v_cvt_pk_bf16_f32 v216, v222, v223
	v_add_f32_e32 v164, v223, v164
	s_waitcnt lgkmcnt(3)
	v_mfma_f32_32x32x16_bf16 v[50:65], v[198:201], v[130:133], v[50:65]
	ds_read_b128 v[194:197], v228 offset:40448
	v_exp_f32_e32 v224, v104
	v_exp_f32_e32 v225, v105
	v_add_f32_e32 v164, v224, v164
	v_cvt_pk_bf16_f32 v217, v224, v225
	v_add_f32_e32 v164, v225, v164
	s_waitcnt lgkmcnt(3)
	v_mfma_f32_32x32x16_bf16 v[34:49], v[182:185], v[134:137], v[34:49]
	ds_read_b128 v[198:201], v228 offset:35872
	v_exp_f32_e32 v222, v106
	v_exp_f32_e32 v223, v107
	v_add_f32_e32 v164, v222, v164
	v_cvt_pk_bf16_f32 v218, v222, v223
	v_add_f32_e32 v164, v223, v164
	s_mov_b32 s13, s20
	s_mov_b32 s20, s19
	s_add_i32 s19, s19, 1
	s_cmp_eq_u32 s19, s9
	s_cselect_b32 s19, 0, s19
	s_waitcnt lgkmcnt(3)
	v_mfma_f32_32x32x16_bf16 v[50:65], v[186:189], v[134:137], v[50:65]
	ds_read_b128 v[182:185], v228 offset:40480
	v_exp_f32_e32 v224, v108
	v_exp_f32_e32 v225, v109
	v_add_f32_e32 v164, v224, v164
	v_cvt_pk_bf16_f32 v219, v224, v225
	v_add_f32_e32 v164, v225, v164
	s_waitcnt vmcnt(2)
	ds_write_b128 v172, v[150:153]
	v_lshl_add_u32 v222, s19, 17, v178
	global_load_dwordx4 v[150:153], v222, s[52:53]
	s_waitcnt lgkmcnt(4)
	v_mfma_f32_32x32x16_bf16 v[2:17], v[190:193], v[206:209], v[2:17]
	ds_read_b128 v[186:189], v228 offset:35904
	v_exp_f32_e32 v222, v110
	v_exp_f32_e32 v223, v111
	v_add_f32_e32 v164, v222, v164
	v_cvt_pk_bf16_f32 v220, v222, v223
	v_add_f32_e32 v164, v223, v164
	s_and_b64 vcc, exec, s[2:3]
	s_cbranch_vccz .Lmla_p1_nope
	ds_write_b128 v176, v[160:163] offset:128
	v_lshl_add_u32 v222, s19, 12, v179
	global_load_dwordx4 v[160:163], v222, s[62:63]
.Lmla_p1_nope:
	s_waitcnt lgkmcnt(4)
	v_mfma_f32_32x32x16_bf16 v[18:33], v[194:197], v[206:209], v[18:33]
	ds_read_b128 v[190:193], v228 offset:40512
	v_exp_f32_e32 v224, v112
	v_exp_f32_e32 v225, v113
	v_add_f32_e32 v164, v224, v164
	v_cvt_pk_bf16_f32 v221, v224, v225
	v_add_f32_e32 v164, v225, v164
	v_add_u32_e32 v222, 0xb000, v173
	ds_write_b128 v222, v[202:205] offset:49152
	v_lshl_add_u32 v222, s13, 7, v168
	global_load_dwordx4 v[202:205], v222, s[56:57]
	s_waitcnt lgkmcnt(5)
	v_mfma_f32_32x32x16_bf16 v[2:17], v[198:201], v[210:213], v[2:17]
	ds_read_b128 v[194:197], v228 offset:35936
	v_max3_f32 v224, v34, v35, v36
	v_max3_f32 v225, v50, v51, v52
	v_max3_f32 v224, v224, v37, v38
	v_max3_f32 v225, v225, v53, v54
	s_waitcnt lgkmcnt(5)
	v_mfma_f32_32x32x16_bf16 v[18:33], v[182:185], v[210:213], v[18:33]
	ds_read_b128 v[198:201], v228 offset:40544
	ds_read_b128 v[182:185], v229 offset:13312
	v_max3_f32 v224, v224, v39, v40
	v_max3_f32 v225, v225, v55, v56
	v_max3_f32 v224, v224, v41, v42
	v_max3_f32 v225, v225, v57, v58
	s_waitcnt lgkmcnt(5)
	v_mfma_f32_32x32x16_bf16 v[2:17], v[186:189], v[214:217], v[2:17]
	ds_read_b128 v[186:189], v229 offset:19968
	v_max3_f32 v224, v224, v43, v44
	v_max3_f32 v225, v225, v59, v60
	v_max3_f32 v224, v224, v45, v46
	v_max3_f32 v225, v225, v61, v62
	s_waitcnt lgkmcnt(5)
	v_mfma_f32_32x32x16_bf16 v[18:33], v[190:193], v[214:217], v[18:33]
	ds_read_b128 v[190:193], v229 offset:13344
	v_max3_f32 v224, v224, v47, v48
	v_max3_f32 v225, v225, v63, v64
	v_max3_f32 v224, v224, v49, v65
	v_max_f32_e32 v224, v224, v225
	s_waitcnt lgkmcnt(4)
	v_mfma_f32_32x32x16_bf16 v[2:17], v[194:197], v[218:221], v[2:17]
	ds_read_b128 v[194:197], v229 offset:20000
	v_mov_b32_e32 v225, v224
	v_add_f32_e32 v1, v1, v164
	s_add_i32 s11, s11, 1
	v_permlane32_swap_b32_e32 v224, v225
	s_cmp_eq_u32 s9, s11
	v_max_f32_e32 v167, v224, v225
	v_cmp_lt_f32_e32 vcc, s66, v167
	s_waitcnt lgkmcnt(4)
	v_mfma_f32_32x32x16_bf16 v[18:33], v[198:201], v[218:221], v[18:33]
	s_waitcnt lgkmcnt(6)
	s_barrier

; #define SB() __builtin_amdgcn_sched_barrier(0)
; template <int VAR>
; __device__ __forceinline__ void attn_phase(LAS unsigned char* lds, const AttnP P, int vcu, int G, int wave_s) {
;     ...
;                 if (ND0 == 6) {
;                     KR1(0); KR1(1); KR1(2); KR1(3); SB();
;                     QK1(0, negm); EX2(pc0, 0, w0.x); KR1(4); SB();
;                     QK1(1, negm); EX2(pc0, 2, w0.y); KR1(5); SB();
;                     QK1(2, pn0); EX2(pc0, 4, w0.z); KR1(6); SB();
;                     QK1(3, pn1); EX2(pc0, 6, w0.w); KR1(7); SB();
;                     QK1(4, pn0); EX2(pc0, 8, w1.x); KR1(8); SB();
;                     QK1(5, pn1); EX2(pc0, 10, w1.y); KR1(9); SB();
;                     QK1(6, pn0); EX2(pc0, 12, w1.z); KR1(10); SB();
;                     QK1(7, pn1); EX2(pc0, 14, w1.w); KR1(11); SB();
;                     QK1(8, pn0); EX2(pc1, 0, w2.x); VR1(0); SB();
;                     QK1(9, pn1); EX2(pc1, 2, w2.y); VR1(1); SB();
;                     QK1(10, pn0); EX2(pc1, 4, w2.z); VR1(2); SB();
;                     QK1(11, pn1); EX2(pc1, 6, w2.w); VR1(3); SB();
;                 } else {
;                     KR1(0); KR1(1); KR1(2); KR1(3); SB();
;                     QK1(0, negm); EX2(pc0, 0, w0.x); EX2(pc0, 2, w0.y); KR1(4); SB();
;                     QK1(1, negm); EX2(pc0, 4, w0.z); EX2(pc0, 6, w0.w); KR1(5); SB();
;                     QK1(2, pn0); EX2(pc0, 8, w1.x); EX2(pc0, 10, w1.y); KR1(6); SB();
;                     QK1(3, pn1); EX2(pc0, 12, w1.z); EX2(pc0, 14, w1.w); KR1(7); SB();
;                     QK1(4, pn0); EX2(pc1, 0, w2.x); VR1(0); SB();
;                     QK1(5, pn1); EX2(pc1, 2, w2.y); VR1(1); SB();
;                     QK1(6, pn0); EX2(pc1, 4, w2.z); VR1(2); SB();
;                     QK1(7, pn1); EX2(pc1, 6, w2.w); VR1(3); SB();
;                 }
;                 PV1(0, w0); EX2(pc1, 8, w3.x); VR1(4); SB();
;                 PV1(1, w0); EX2(pc1, 10, w3.y); VR1(5); SB();
;                 PV1(2, w1); EX2(pc1, 12, w3.z); VR1(6); SB();
;                 PV1(3, w1); EX2(pc1, 14, w3.w); VR1(7); SB();
;                 lrun += sacc;
;                 PV1(4, w2); MASK_TILE(pn0, pn1, t + 1); SB();
;                 PV1(5, w2); SB();
;                 PV1(6, w3); SB();
;                 PV1(7, w3); rmn = rowmax32(pn0, pn1); if (!USE_NEGM) rmn -= mref; SB();
.Lmla_p3_go:
	v_exp_f32_e32 v222, v82
	v_exp_f32_e32 v223, v83
	v_add_f32_e32 v164, 0, v222
	v_cvt_pk_bf16_f32 v206, v222, v223
	v_add_f32_e32 v164, v223, v164
	v_exp_f32_e32 v224, v84
	v_exp_f32_e32 v225, v85
	v_add_f32_e32 v164, v224, v164
	v_cvt_pk_bf16_f32 v207, v224, v225
	v_add_f32_e32 v164, v225, v164
	s_waitcnt lgkmcnt(4)
	v_mfma_f32_32x32x16_bf16 v[34:49], v[182:185], v[114:117], v[66:81]
	ds_read_b128 v[198:201], v229 offset:26688
	v_exp_f32_e32 v222, v86
	v_exp_f32_e32 v223, v87
	v_add_f32_e32 v164, v222, v164
	v_cvt_pk_bf16_f32 v208, v222, v223
	v_add_f32_e32 v164, v223, v164
	s_waitcnt lgkmcnt(4)
	v_mfma_f32_32x32x16_bf16 v[50:65], v[186:189], v[114:117], v[66:81]
	ds_read_b128 v[182:185], v229 offset:33344
	v_exp_f32_e32 v224, v88
	v_exp_f32_e32 v225, v89
	v_add_f32_e32 v164, v224, v164
	v_cvt_pk_bf16_f32 v209, v224, v225
	v_add_f32_e32 v164, v225, v164
	s_waitcnt lgkmcnt(3)
	v_mfma_f32_32x32x16_bf16 v[34:49], v[190:193], v[118:121], v[34:49]
	ds_read_b128 v[186:189], v229 offset:26720
	v_exp_f32_e32 v222, v90
	v_exp_f32_e32 v223, v91
	v_add_f32_e32 v164, v222, v164
	v_cvt_pk_bf16_f32 v210, v222, v223
	v_add_f32_e32 v164, v223, v164
	s_waitcnt lgkmcnt(3)
	v_mfma_f32_32x32x16_bf16 v[50:65], v[194:197], v[118:121], v[50:65]
	ds_read_b128 v[190:193], v229 offset:33376
	v_exp_f32_e32 v224, v92
	v_exp_f32_e32 v225, v93
	v_add_f32_e32 v164, v224, v164
	v_cvt_pk_bf16_f32 v211, v224, v225
	v_add_f32_e32 v164, v225, v164
	s_waitcnt lgkmcnt(3)
	v_mfma_f32_32x32x16_bf16 v[34:49], v[198:201], v[122:125], v[34:49]
	ds_read_b128 v[194:197], v229 offset:26752
	v_exp_f32_e32 v222, v94
	v_exp_f32_e32 v223, v95
	v_add_f32_e32 v164, v222, v164
	v_cvt_pk_bf16_f32 v212, v222, v223
	v_add_f32_e32 v164, v223, v164
	s_waitcnt lgkmcnt(3)
	v_mfma_f32_32x32x16_bf16 v[50:65], v[182:185], v[122:125], v[50:65]
	ds_read_b128 v[198:201], v229 offset:33408
	v_exp_f32_e32 v224, v96
	v_exp_f32_e32 v225, v97
	v_add_f32_e32 v164, v224, v164
	v_cvt_pk_bf16_f32 v213, v224, v225
	v_add_f32_e32 v164, v225, v164
	s_waitcnt lgkmcnt(3)
	v_mfma_f32_32x32x16_bf16 v[34:49], v[186:189], v[126:129], v[34:49]
	ds_read_b128 v[182:185], v229 offset:26784
	v_exp_f32_e32 v222, v98
	v_exp_f32_e32 v223, v99
	v_add_f32_e32 v164, v222, v164
	v_cvt_pk_bf16_f32 v214, v222, v223
	v_add_f32_e32 v164, v223, v164
	s_waitcnt lgkmcnt(3)
	v_mfma_f32_32x32x16_bf16 v[50:65], v[190:193], v[126:129], v[50:65]
	ds_read_b128 v[186:189], v229 offset:33440
	v_exp_f32_e32 v224, v100
	v_exp_f32_e32 v225, v101
	v_add_f32_e32 v164, v224, v164
	v_cvt_pk_bf16_f32 v215, v224, v225
	v_add_f32_e32 v164, v225, v164
	s_waitcnt lgkmcnt(3)
	v_mfma_f32_32x32x16_bf16 v[34:49], v[194:197], v[130:133], v[34:49]
	ds_read_b128 v[190:193], v181 offset:49152
	v_exp_f32_e32 v222, v102
	v_exp_f32_e32 v223, v103
	v_add_f32_e32 v164, v222, v164
	v_cvt_pk_bf16_f32 v216, v222, v223
	v_add_f32_e32 v164, v223, v164
	s_waitcnt lgkmcnt(3)
	v_mfma_f32_32x32x16_bf16 v[50:65], v[198:201], v[130:133], v[50:65]
	ds_read_b128 v[194:197], v181 offset:53760
	v_exp_f32_e32 v224, v104
	v_exp_f32_e32 v225, v105
	v_add_f32_e32 v164, v224, v164
	v_cvt_pk_bf16_f32 v217, v224, v225
	v_add_f32_e32 v164, v225, v164
	s_waitcnt lgkmcnt(3)
	v_mfma_f32_32x32x16_bf16 v[34:49], v[182:185], v[134:137], v[34:49]
	ds_read_b128 v[198:201], v181 offset:49184
	v_exp_f32_e32 v222, v106
	v_exp_f32_e32 v223, v107
	v_add_f32_e32 v164, v222, v164
	v_cvt_pk_bf16_f32 v218, v222, v223
	v_add_f32_e32 v164, v223, v164
	s_mov_b32 s13, s20
	s_mov_b32 s20, s19
	s_add_i32 s19, s19, 1
	s_cmp_eq_u32 s19, s9
	s_cselect_b32 s19, 0, s19
	s_waitcnt lgkmcnt(3)
	v_mfma_f32_32x32x16_bf16 v[50:65], v[186:189], v[134:137], v[50:65]
	ds_read_b128 v[182:185], v181 offset:53792
	v_exp_f32_e32 v224, v108
	v_exp_f32_e32 v225, v109
	v_add_f32_e32 v164, v224, v164
	v_cvt_pk_bf16_f32 v219, v224, v225
	v_add_f32_e32 v164, v225, v164
	s_waitcnt vmcnt(2)
	ds_write_b128 v172, v[150:153] offset:45056
	v_lshl_add_u32 v222, s19, 17, v178
	global_load_dwordx4 v[150:153], v222, s[52:53]
	s_waitcnt lgkmcnt(4)
	v_mfma_f32_32x32x16_bf16 v[2:17], v[190:193], v[206:209], v[2:17]
	ds_read_b128 v[186:189], v181 offset:49216
	v_exp_f32_e32 v222, v110
	v_exp_f32_e32 v223, v111
	v_add_f32_e32 v164, v222, v164
	v_cvt_pk_bf16_f32 v220, v222, v223
	v_add_f32_e32 v164, v223, v164
	s_and_b64 vcc, exec, s[2:3]
	s_cbranch_vccz .Lmla_p3_nope
	ds_write_b128 v176, v[160:163] offset:45184
	v_lshl_add_u32 v222, s19, 12, v179
	global_load_dwordx4 v[160:163], v222, s[62:63]
.Lmla_p3_nope:
	s_waitcnt lgkmcnt(4)
	v_mfma_f32_32x32x16_bf16 v[18:33], v[194:197], v[206:209], v[18:33]
	ds_read_b128 v[190:193], v181 offset:53824
	v_exp_f32_e32 v224, v112
	v_exp_f32_e32 v225, v113
	v_add_f32_e32 v164, v224, v164
	v_cvt_pk_bf16_f32 v221, v224, v225
	v_add_f32_e32 v164, v225, v164
	ds_write_b128 v173, v[202:205] offset:35840
	v_lshl_add_u32 v222, s13, 7, v168
	global_load_dwordx4 v[202:205], v222, s[56:57]
	s_waitcnt lgkmcnt(5)
	v_mfma_f32_32x32x16_bf16 v[2:17], v[198:201], v[210:213], v[2:17]
	ds_read_b128 v[194:197], v181 offset:49248
	v_max3_f32 v224, v34, v35, v36
	v_max3_f32 v225, v50, v51, v52
	v_max3_f32 v224, v224, v37, v38
	v_max3_f32 v225, v225, v53, v54
	s_waitcnt lgkmcnt(5)
	v_mfma_f32_32x32x16_bf16 v[18:33], v[182:185], v[210:213], v[18:33]
	ds_read_b128 v[198:201], v181 offset:53856
	ds_read_b128 v[182:185], v174
	v_max3_f32 v224, v224, v39, v40
	v_max3_f32 v225, v225, v55, v56
	v_max3_f32 v224, v224, v41, v42
	v_max3_f32 v225, v225, v57, v58
	s_waitcnt lgkmcnt(5)
	v_mfma_f32_32x32x16_bf16 v[2:17], v[186:189], v[214:217], v[2:17]
	ds_read_b128 v[186:189], v174 offset:6656
	v_max3_f32 v224, v224, v43, v44
	v_max3_f32 v225, v225, v59, v60
	v_max3_f32 v224, v224, v45, v46
	v_max3_f32 v225, v225, v61, v62
	s_waitcnt lgkmcnt(5)
	v_mfma_f32_32x32x16_bf16 v[18:33], v[190:193], v[214:217], v[18:33]
	ds_read_b128 v[190:193], v174 offset:32
	v_max3_f32 v224, v224, v47, v48
	v_max3_f32 v225, v225, v63, v64
	v_max3_f32 v224, v224, v49, v65
	v_max_f32_e32 v224, v224, v225
	s_waitcnt lgkmcnt(4)
	v_mfma_f32_32x32x16_bf16 v[2:17], v[194:197], v[218:221], v[2:17]
	ds_read_b128 v[194:197], v174 offset:6688
	v_mov_b32_e32 v225, v224
	v_add_f32_e32 v1, v1, v164
	s_add_i32 s11, s11, 1
	v_permlane32_swap_b32_e32 v224, v225
	s_cmp_eq_u32 s9, s11
	v_max_f32_e32 v167, v224, v225
	v_cmp_lt_f32_e32 vcc, s66, v167
	s_waitcnt lgkmcnt(4)
	v_mfma_f32_32x32x16_bf16 v[18:33], v[198:201], v[218:221], v[18:33]
	s_waitcnt lgkmcnt(6)
	s_barrier

; #define SB() __builtin_amdgcn_sched_barrier(0)
; template <int VAR>
; __device__ __forceinline__ void attn_phase(LAS unsigned char* lds, const AttnP P, int vcu, int G, int wave_s) {
;     ...
;                 if (ND0 == 6) {
;                     KR1(0); KR1(1); KR1(2); KR1(3); SB();
;                     QK1(0, negm); EX2(pc0, 0, w0.x); KR1(4); SB();
;                     QK1(1, negm); EX2(pc0, 2, w0.y); KR1(5); SB();
;                     QK1(2, pn0); EX2(pc0, 4, w0.z); KR1(6); SB();
;                     QK1(3, pn1); EX2(pc0, 6, w0.w); KR1(7); SB();
;                     QK1(4, pn0); EX2(pc0, 8, w1.x); KR1(8); SB();
;                     QK1(5, pn1); EX2(pc0, 10, w1.y); KR1(9); SB();
;                     QK1(6, pn0); EX2(pc0, 12, w1.z); KR1(10); SB();
;                     QK1(7, pn1); EX2(pc0, 14, w1.w); KR1(11); SB();
;                     QK1(8, pn0); EX2(pc1, 0, w2.x); VR1(0); SB();
;                     QK1(9, pn1); EX2(pc1, 2, w2.y); VR1(1); SB();
;                     QK1(10, pn0); EX2(pc1, 4, w2.z); VR1(2); SB();
;                     QK1(11, pn1); EX2(pc1, 6, w2.w); VR1(3); SB();
;                 } else {
;                     KR1(0); KR1(1); KR1(2); KR1(3); SB();
;                     QK1(0, negm); EX2(pc0, 0, w0.x); EX2(pc0, 2, w0.y); KR1(4); SB();
;                     QK1(1, negm); EX2(pc0, 4, w0.z); EX2(pc0, 6, w0.w); KR1(5); SB();
;                     QK1(2, pn0); EX2(pc0, 8, w1.x); EX2(pc0, 10, w1.y); KR1(6); SB();
;                     QK1(3, pn1); EX2(pc0, 12, w1.z); EX2(pc0, 14, w1.w); KR1(7); SB();
;                     QK1(4, pn0); EX2(pc1, 0, w2.x); VR1(0); SB();
;                     QK1(5, pn1); EX2(pc1, 2, w2.y); VR1(1); SB();
;                     QK1(6, pn0); EX2(pc1, 4, w2.z); VR1(2); SB();
;                     QK1(7, pn1); EX2(pc1, 6, w2.w); VR1(3); SB();
;                 }
;                 PV1(0, w0); EX2(pc1, 8, w3.x); VR1(4); SB();
;                 PV1(1, w0); EX2(pc1, 10, w3.y); VR1(5); SB();
;                 PV1(2, w1); EX2(pc1, 12, w3.z); VR1(6); SB();
;                 PV1(3, w1); EX2(pc1, 14, w3.w); VR1(7); SB();
;                 lrun += sacc;
;                 PV1(4, w2); MASK_TILE(pn0, pn1, t + 1); SB();
;                 PV1(5, w2); SB();
;                 PV1(6, w3); SB();
;                 PV1(7, w3); rmn = rowmax32(pn0, pn1); if (!USE_NEGM) rmn -= mref; SB();
.Lmla_p5_go:
	v_exp_f32_e32 v222, v82
	v_exp_f32_e32 v223, v83
	v_add_f32_e32 v164, 0, v222
	v_cvt_pk_bf16_f32 v206, v222, v223
	v_add_f32_e32 v164, v223, v164
	v_exp_f32_e32 v224, v84
	v_exp_f32_e32 v225, v85
	v_add_f32_e32 v164, v224, v164
	v_cvt_pk_bf16_f32 v207, v224, v225
	v_add_f32_e32 v164, v225, v164
	s_waitcnt lgkmcnt(4)
	v_mfma_f32_32x32x16_bf16 v[34:49], v[182:185], v[114:117], v[66:81]
	ds_read_b128 v[198:201], v174 offset:22592
	v_exp_f32_e32 v222, v86
	v_exp_f32_e32 v223, v87
	v_add_f32_e32 v164, v222, v164
	v_cvt_pk_bf16_f32 v208, v222, v223
	v_add_f32_e32 v164, v223, v164
	s_waitcnt lgkmcnt(4)
	v_mfma_f32_32x32x16_bf16 v[50:65], v[186:189], v[114:117], v[66:81]
	ds_read_b128 v[182:185], v174 offset:29248
	v_exp_f32_e32 v224, v88
	v_exp_f32_e32 v225, v89
	v_add_f32_e32 v164, v224, v164
	v_cvt_pk_bf16_f32 v209, v224, v225
	v_add_f32_e32 v164, v225, v164
	s_waitcnt lgkmcnt(3)
	v_mfma_f32_32x32x16_bf16 v[34:49], v[190:193], v[118:121], v[34:49]
	ds_read_b128 v[186:189], v174 offset:22624
	v_exp_f32_e32 v222, v90
	v_exp_f32_e32 v223, v91
	v_add_f32_e32 v164, v222, v164
	v_cvt_pk_bf16_f32 v210, v222, v223
	v_add_f32_e32 v164, v223, v164
	s_waitcnt lgkmcnt(3)
	v_mfma_f32_32x32x16_bf16 v[50:65], v[194:197], v[118:121], v[50:65]
	ds_read_b128 v[190:193], v174 offset:29280
	v_exp_f32_e32 v224, v92
	v_exp_f32_e32 v225, v93
	v_add_f32_e32 v164, v224, v164
	v_cvt_pk_bf16_f32 v211, v224, v225
	v_add_f32_e32 v164, v225, v164
	s_waitcnt lgkmcnt(3)
	v_mfma_f32_32x32x16_bf16 v[34:49], v[198:201], v[122:125], v[34:49]
	ds_read_b128 v[194:197], v174 offset:22656
	v_exp_f32_e32 v222, v94
	v_exp_f32_e32 v223, v95
	v_add_f32_e32 v164, v222, v164
	v_cvt_pk_bf16_f32 v212, v222, v223
	v_add_f32_e32 v164, v223, v164
	s_waitcnt lgkmcnt(3)
	v_mfma_f32_32x32x16_bf16 v[50:65], v[182:185], v[122:125], v[50:65]
	ds_read_b128 v[198:201], v174 offset:29312
	v_exp_f32_e32 v224, v96
	v_exp_f32_e32 v225, v97
	v_add_f32_e32 v164, v224, v164
	v_cvt_pk_bf16_f32 v213, v224, v225
	v_add_f32_e32 v164, v225, v164
	s_waitcnt lgkmcnt(3)
	v_mfma_f32_32x32x16_bf16 v[34:49], v[186:189], v[126:129], v[34:49]
	ds_read_b128 v[182:185], v174 offset:22688
	v_exp_f32_e32 v222, v98
	v_exp_f32_e32 v223, v99
	v_add_f32_e32 v164, v222, v164
	v_cvt_pk_bf16_f32 v214, v222, v223
	v_add_f32_e32 v164, v223, v164
	s_waitcnt lgkmcnt(3)
	v_mfma_f32_32x32x16_bf16 v[50:65], v[190:193], v[126:129], v[50:65]
	ds_read_b128 v[186:189], v174 offset:29344
	v_exp_f32_e32 v224, v100
	v_exp_f32_e32 v225, v101
	v_add_f32_e32 v164, v224, v164
	v_cvt_pk_bf16_f32 v215, v224, v225
	v_add_f32_e32 v164, v225, v164
	s_waitcnt lgkmcnt(3)
	v_mfma_f32_32x32x16_bf16 v[34:49], v[194:197], v[130:133], v[34:49]
	ds_read_b128 v[190:193], v228 offset:35840
	v_exp_f32_e32 v222, v102
	v_exp_f32_e32 v223, v103
	v_add_f32_e32 v164, v222, v164
	v_cvt_pk_bf16_f32 v216, v222, v223
	v_add_f32_e32 v164, v223, v164
	s_waitcnt lgkmcnt(3)
	v_mfma_f32_32x32x16_bf16 v[50:65], v[198:201], v[130:133], v[50:65]
	ds_read_b128 v[194:197], v228 offset:40448
	v_exp_f32_e32 v224, v104
	v_exp_f32_e32 v225, v105
	v_add_f32_e32 v164, v224, v164
	v_cvt_pk_bf16_f32 v217, v224, v225
	v_add_f32_e32 v164, v225, v164
	s_waitcnt lgkmcnt(3)
	v_mfma_f32_32x32x16_bf16 v[34:49], v[182:185], v[134:137], v[34:49]
	ds_read_b128 v[198:201], v228 offset:35872
	v_exp_f32_e32 v222, v106
	v_exp_f32_e32 v223, v107
	v_add_f32_e32 v164, v222, v164
	v_cvt_pk_bf16_f32 v218, v222, v223
	v_add_f32_e32 v164, v223, v164
	s_mov_b32 s13, s20
	s_mov_b32 s20, s19
	s_add_i32 s19, s19, 1
	s_cmp_eq_u32 s19, s9
	s_cselect_b32 s19, 0, s19
	s_waitcnt lgkmcnt(3)
	v_mfma_f32_32x32x16_bf16 v[50:65], v[186:189], v[134:137], v[50:65]
	ds_read_b128 v[182:185], v228 offset:40480
	v_exp_f32_e32 v224, v108
	v_exp_f32_e32 v225, v109
	v_add_f32_e32 v164, v224, v164
	v_cvt_pk_bf16_f32 v219, v224, v225
	v_add_f32_e32 v164, v225, v164
	s_waitcnt vmcnt(2)
	v_add_u32_e32 v222, 0xb000, v172
	ds_write_b128 v222, v[150:153] offset:26624
	v_lshl_add_u32 v222, s19, 17, v178
	global_load_dwordx4 v[150:153], v222, s[52:53]
	s_waitcnt lgkmcnt(4)
	v_mfma_f32_32x32x16_bf16 v[2:17], v[190:193], v[206:209], v[2:17]
	ds_read_b128 v[186:189], v228 offset:35904
	v_exp_f32_e32 v222, v110
	v_exp_f32_e32 v223, v111
	v_add_f32_e32 v164, v222, v164
	v_cvt_pk_bf16_f32 v220, v222, v223
	v_add_f32_e32 v164, v223, v164
	s_and_b64 vcc, exec, s[2:3]
	s_cbranch_vccz .Lmla_p5_nope
	v_add_u32_e32 v222, 0xb000, v176
	ds_write_b128 v222, v[160:163] offset:26752
	v_lshl_add_u32 v222, s19, 12, v179
	global_load_dwordx4 v[160:163], v222, s[62:63]
.Lmla_p5_nope:
	s_waitcnt lgkmcnt(4)
	v_mfma_f32_32x32x16_bf16 v[18:33], v[194:197], v[206:209], v[18:33]
	ds_read_b128 v[190:193], v228 offset:40512
	v_exp_f32_e32 v224, v112
	v_exp_f32_e32 v225, v113
	v_add_f32_e32 v164, v224, v164
	v_cvt_pk_bf16_f32 v221, v224, v225
	v_add_f32_e32 v164, v225, v164
	v_add_u32_e32 v222, 0xb000, v173
	ds_write_b128 v222, v[202:205] offset:49152
	v_lshl_add_u32 v222, s13, 7, v168
	global_load_dwordx4 v[202:205], v222, s[56:57]
	s_waitcnt lgkmcnt(5)
	v_mfma_f32_32x32x16_bf16 v[2:17], v[198:201], v[210:213], v[2:17]
	ds_read_b128 v[194:197], v228 offset:35936
	v_max3_f32 v224, v34, v35, v36
	v_max3_f32 v225, v50, v51, v52
	v_max3_f32 v224, v224, v37, v38
	v_max3_f32 v225, v225, v53, v54
	s_waitcnt lgkmcnt(5)
	v_mfma_f32_32x32x16_bf16 v[18:33], v[182:185], v[210:213], v[18:33]
	ds_read_b128 v[198:201], v228 offset:40544
	ds_read_b128 v[182:185], v174 offset:45056
	v_max3_f32 v224, v224, v39, v40
	v_max3_f32 v225, v225, v55, v56
	v_max3_f32 v224, v224, v41, v42
	v_max3_f32 v225, v225, v57, v58
	s_waitcnt lgkmcnt(5)
	v_mfma_f32_32x32x16_bf16 v[2:17], v[186:189], v[214:217], v[2:17]
	ds_read_b128 v[186:189], v174 offset:51712
	v_max3_f32 v224, v224, v43, v44
	v_max3_f32 v225, v225, v59, v60
	v_max3_f32 v224, v224, v45, v46
	v_max3_f32 v225, v225, v61, v62
	s_waitcnt lgkmcnt(5)
	v_mfma_f32_32x32x16_bf16 v[18:33], v[190:193], v[214:217], v[18:33]
	ds_read_b128 v[190:193], v174 offset:45088
	v_max3_f32 v224, v224, v47, v48
	v_max3_f32 v225, v225, v63, v64
	v_max3_f32 v224, v224, v49, v65
	v_max_f32_e32 v224, v224, v225
	s_waitcnt lgkmcnt(4)
	v_mfma_f32_32x32x16_bf16 v[2:17], v[194:197], v[218:221], v[2:17]
	ds_read_b128 v[194:197], v174 offset:51744
	v_mov_b32_e32 v225, v224
	v_add_f32_e32 v1, v1, v164
	s_add_i32 s11, s11, 1
	v_permlane32_swap_b32_e32 v224, v225
	s_cmp_eq_u32 s9, s11
	v_max_f32_e32 v167, v224, v225
	v_cmp_lt_f32_e32 vcc, s66, v167
	s_waitcnt lgkmcnt(4)
	v_mfma_f32_32x32x16_bf16 v[18:33], v[198:201], v[218:221], v[18:33]
	s_waitcnt lgkmcnt(6)
	s_barrier

; #define SB() __builtin_amdgcn_sched_barrier(0)
; template <int VAR>
; __device__ __forceinline__ void attn_phase(LAS unsigned char* lds, const AttnP P, int vcu, int G, int wave_s) {
;     ...
;                 if (ND0 == 6) {
;                     KR1(0); KR1(1); KR1(2); KR1(3); SB();
;                     QK1(0, negm); EX2(pc0, 0, w0.x); KR1(4); SB();
;                     QK1(1, negm); EX2(pc0, 2, w0.y); KR1(5); SB();
;                     QK1(2, pn0); EX2(pc0, 4, w0.z); KR1(6); SB();
;                     QK1(3, pn1); EX2(pc0, 6, w0.w); KR1(7); SB();
;                     QK1(4, pn0); EX2(pc0, 8, w1.x); KR1(8); SB();
;                     QK1(5, pn1); EX2(pc0, 10, w1.y); KR1(9); SB();
;                     QK1(6, pn0); EX2(pc0, 12, w1.z); KR1(10); SB();
;                     QK1(7, pn1); EX2(pc0, 14, w1.w); KR1(11); SB();
;                     QK1(8, pn0); EX2(pc1, 0, w2.x); VR1(0); SB();
;                     QK1(9, pn1); EX2(pc1, 2, w2.y); VR1(1); SB();
;                     QK1(10, pn0); EX2(pc1, 4, w2.z); VR1(2); SB();
;                     QK1(11, pn1); EX2(pc1, 6, w2.w); VR1(3); SB();
;                 } else {
;                     KR1(0); KR1(1); KR1(2); KR1(3); SB();
;                     QK1(0, negm); EX2(pc0, 0, w0.x); EX2(pc0, 2, w0.y); KR1(4); SB();
;                     QK1(1, negm); EX2(pc0, 4, w0.z); EX2(pc0, 6, w0.w); KR1(5); SB();
;                     QK1(2, pn0); EX2(pc0, 8, w1.x); EX2(pc0, 10, w1.y); KR1(6); SB();
;                     QK1(3, pn1); EX2(pc0, 12, w1.z); EX2(pc0, 14, w1.w); KR1(7); SB();
;                     QK1(4, pn0); EX2(pc1, 0, w2.x); VR1(0); SB();
;                     QK1(5, pn1); EX2(pc1, 2, w2.y); VR1(1); SB();
;                     QK1(6, pn0); EX2(pc1, 4, w2.z); VR1(2); SB();
;                     QK1(7, pn1); EX2(pc1, 6, w2.w); VR1(3); SB();
;                 }
;                 PV1(0, w0); EX2(pc1, 8, w3.x); VR1(4); SB();
;                 PV1(1, w0); EX2(pc1, 10, w3.y); VR1(5); SB();
;                 PV1(2, w1); EX2(pc1, 12, w3.z); VR1(6); SB();
;                 PV1(3, w1); EX2(pc1, 14, w3.w); VR1(7); SB();
;                 lrun += sacc;
;                 PV1(4, w2); MASK_TILE(pn0, pn1, t + 1); SB();
;                 PV1(5, w2); SB();
;                 PV1(6, w3); SB();
;                 PV1(7, w3); rmn = rowmax32(pn0, pn1); if (!USE_NEGM) rmn -= mref; SB();
.Lmla_p7_go:
	v_exp_f32_e32 v222, v82
	v_exp_f32_e32 v223, v83
	v_add_f32_e32 v164, 0, v222
	v_cvt_pk_bf16_f32 v206, v222, v223
	v_add_f32_e32 v164, v223, v164
	v_exp_f32_e32 v224, v84
	v_exp_f32_e32 v225, v85
	v_add_f32_e32 v164, v224, v164
	v_cvt_pk_bf16_f32 v207, v224, v225
	v_add_f32_e32 v164, v225, v164
	s_waitcnt lgkmcnt(4)
	v_mfma_f32_32x32x16_bf16 v[34:49], v[182:185], v[114:117], v[66:81]
	ds_read_b128 v[198:201], v229 offset:13376
	v_exp_f32_e32 v222, v86
	v_exp_f32_e32 v223, v87
	v_add_f32_e32 v164, v222, v164
	v_cvt_pk_bf16_f32 v208, v222, v223
	v_add_f32_e32 v164, v223, v164
	s_waitcnt lgkmcnt(4)
	v_mfma_f32_32x32x16_bf16 v[50:65], v[186:189], v[114:117], v[66:81]
	ds_read_b128 v[182:185], v229 offset:20032
	v_exp_f32_e32 v224, v88
	v_exp_f32_e32 v225, v89
	v_add_f32_e32 v164, v224, v164
	v_cvt_pk_bf16_f32 v209, v224, v225
	v_add_f32_e32 v164, v225, v164
	s_waitcnt lgkmcnt(3)
	v_mfma_f32_32x32x16_bf16 v[34:49], v[190:193], v[118:121], v[34:49]
	ds_read_b128 v[186:189], v229 offset:13408
	v_exp_f32_e32 v222, v90
	v_exp_f32_e32 v223, v91
	v_add_f32_e32 v164, v222, v164
	v_cvt_pk_bf16_f32 v210, v222, v223
	v_add_f32_e32 v164, v223, v164
	s_waitcnt lgkmcnt(3)
	v_mfma_f32_32x32x16_bf16 v[50:65], v[194:197], v[118:121], v[50:65]
	ds_read_b128 v[190:193], v229 offset:20064
	v_exp_f32_e32 v224, v92
	v_exp_f32_e32 v225, v93
	v_add_f32_e32 v164, v224, v164
	v_cvt_pk_bf16_f32 v211, v224, v225
	v_add_f32_e32 v164, v225, v164
	s_waitcnt lgkmcnt(3)
	v_mfma_f32_32x32x16_bf16 v[34:49], v[198:201], v[122:125], v[34:49]
	ds_read_b128 v[194:197], v229 offset:13440
	v_exp_f32_e32 v222, v94
	v_exp_f32_e32 v223, v95
	v_add_f32_e32 v164, v222, v164
	v_cvt_pk_bf16_f32 v212, v222, v223
	v_add_f32_e32 v164, v223, v164
	s_waitcnt lgkmcnt(3)
	v_mfma_f32_32x32x16_bf16 v[50:65], v[182:185], v[122:125], v[50:65]
	ds_read_b128 v[198:201], v229 offset:20096
	v_exp_f32_e32 v224, v96
	v_exp_f32_e32 v225, v97
	v_add_f32_e32 v164, v224, v164
	v_cvt_pk_bf16_f32 v213, v224, v225
	v_add_f32_e32 v164, v225, v164
	s_waitcnt lgkmcnt(3)
	v_mfma_f32_32x32x16_bf16 v[34:49], v[186:189], v[126:129], v[34:49]
	ds_read_b128 v[182:185], v229 offset:13472
	v_exp_f32_e32 v222, v98
	v_exp_f32_e32 v223, v99
	v_add_f32_e32 v164, v222, v164
	v_cvt_pk_bf16_f32 v214, v222, v223
	v_add_f32_e32 v164, v223, v164
	s_waitcnt lgkmcnt(3)
	v_mfma_f32_32x32x16_bf16 v[50:65], v[190:193], v[126:129], v[50:65]
	ds_read_b128 v[186:189], v229 offset:20128
	v_exp_f32_e32 v224, v100
	v_exp_f32_e32 v225, v101
	v_add_f32_e32 v164, v224, v164
	v_cvt_pk_bf16_f32 v215, v224, v225
	v_add_f32_e32 v164, v225, v164
	s_waitcnt lgkmcnt(3)
	v_mfma_f32_32x32x16_bf16 v[34:49], v[194:197], v[130:133], v[34:49]
	ds_read_b128 v[190:193], v181 offset:49152
	v_exp_f32_e32 v222, v102
	v_exp_f32_e32 v223, v103
	v_add_f32_e32 v164, v222, v164
	v_cvt_pk_bf16_f32 v216, v222, v223
	v_add_f32_e32 v164, v223, v164
	s_waitcnt lgkmcnt(3)
	v_mfma_f32_32x32x16_bf16 v[50:65], v[198:201], v[130:133], v[50:65]
	ds_read_b128 v[194:197], v181 offset:53760
	v_exp_f32_e32 v224, v104
	v_exp_f32_e32 v225, v105
	v_add_f32_e32 v164, v224, v164
	v_cvt_pk_bf16_f32 v217, v224, v225
	v_add_f32_e32 v164, v225, v164
	s_waitcnt lgkmcnt(3)
	v_mfma_f32_32x32x16_bf16 v[34:49], v[182:185], v[134:137], v[34:49]
	ds_read_b128 v[198:201], v181 offset:49184
	v_exp_f32_e32 v222, v106
	v_exp_f32_e32 v223, v107
	v_add_f32_e32 v164, v222, v164
	v_cvt_pk_bf16_f32 v218, v222, v223
	v_add_f32_e32 v164, v223, v164
	s_mov_b32 s13, s20
	s_mov_b32 s20, s19
	s_add_i32 s19, s19, 1
	s_cmp_eq_u32 s19, s9
	s_cselect_b32 s19, 0, s19
	s_waitcnt lgkmcnt(3)
	v_mfma_f32_32x32x16_bf16 v[50:65], v[186:189], v[134:137], v[50:65]
	ds_read_b128 v[182:185], v181 offset:53792
	v_exp_f32_e32 v224, v108
	v_exp_f32_e32 v225, v109
	v_add_f32_e32 v164, v224, v164
	v_cvt_pk_bf16_f32 v219, v224, v225
	v_add_f32_e32 v164, v225, v164
	s_waitcnt vmcnt(2)
	ds_write_b128 v172, v[150:153] offset:22528
	v_lshl_add_u32 v222, s19, 17, v178
	global_load_dwordx4 v[150:153], v222, s[52:53]
	s_waitcnt lgkmcnt(4)
	v_mfma_f32_32x32x16_bf16 v[2:17], v[190:193], v[206:209], v[2:17]
	ds_read_b128 v[186:189], v181 offset:49216
	v_exp_f32_e32 v222, v110
	v_exp_f32_e32 v223, v111
	v_add_f32_e32 v164, v222, v164
	v_cvt_pk_bf16_f32 v220, v222, v223
	v_add_f32_e32 v164, v223, v164
	s_and_b64 vcc, exec, s[2:3]
	s_cbranch_vccz .Lmla_p7_nope
	ds_write_b128 v176, v[160:163] offset:22656
	v_lshl_add_u32 v222, s19, 12, v179
	global_load_dwordx4 v[160:163], v222, s[62:63]
.Lmla_p7_nope:
	s_waitcnt lgkmcnt(4)
	v_mfma_f32_32x32x16_bf16 v[18:33], v[194:197], v[206:209], v[18:33]
	ds_read_b128 v[190:193], v181 offset:53824
	v_exp_f32_e32 v224, v112
	v_exp_f32_e32 v225, v113
	v_add_f32_e32 v164, v224, v164
	v_cvt_pk_bf16_f32 v221, v224, v225
	v_add_f32_e32 v164, v225, v164
	ds_write_b128 v173, v[202:205] offset:35840
	v_lshl_add_u32 v222, s13, 7, v168
	global_load_dwordx4 v[202:205], v222, s[56:57]
	s_waitcnt lgkmcnt(5)
	v_mfma_f32_32x32x16_bf16 v[2:17], v[198:201], v[210:213], v[2:17]
	ds_read_b128 v[194:197], v181 offset:49248
	v_max3_f32 v224, v34, v35, v36
	v_max3_f32 v225, v50, v51, v52
	v_max3_f32 v224, v224, v37, v38
	v_max3_f32 v225, v225, v53, v54
	s_waitcnt lgkmcnt(5)
	v_mfma_f32_32x32x16_bf16 v[18:33], v[182:185], v[210:213], v[18:33]
	ds_read_b128 v[198:201], v181 offset:53856
	ds_read_b128 v[182:185], v229 offset:26624
	v_max3_f32 v224, v224, v39, v40
	v_max3_f32 v225, v225, v55, v56
	v_max3_f32 v224, v224, v41, v42
	v_max3_f32 v225, v225, v57, v58
	s_waitcnt lgkmcnt(5)
	v_mfma_f32_32x32x16_bf16 v[2:17], v[186:189], v[214:217], v[2:17]
	ds_read_b128 v[186:189], v229 offset:33280
	v_max3_f32 v224, v224, v43, v44
	v_max3_f32 v225, v225, v59, v60
	v_max3_f32 v224, v224, v45, v46
	v_max3_f32 v225, v225, v61, v62
	s_waitcnt lgkmcnt(5)
	v_mfma_f32_32x32x16_bf16 v[18:33], v[190:193], v[214:217], v[18:33]
	ds_read_b128 v[190:193], v229 offset:26656
	v_max3_f32 v224, v224, v47, v48
	v_max3_f32 v225, v225, v63, v64
	v_max3_f32 v224, v224, v49, v65
	v_max_f32_e32 v224, v224, v225
	s_waitcnt lgkmcnt(4)
	v_mfma_f32_32x32x16_bf16 v[2:17], v[194:197], v[218:221], v[2:17]
	ds_read_b128 v[194:197], v229 offset:33312
	v_mov_b32_e32 v225, v224
	v_add_f32_e32 v1, v1, v164
	s_add_i32 s11, s11, 1
	v_permlane32_swap_b32_e32 v224, v225
	s_cmp_eq_u32 s9, s11
	v_max_f32_e32 v167, v224, v225
	v_cmp_lt_f32_e32 vcc, s66, v167
	s_waitcnt lgkmcnt(4)
	v_mfma_f32_32x32x16_bf16 v[18:33], v[198:201], v[218:221], v[18:33]
	s_waitcnt lgkmcnt(6)
	s_barrier

; #define SB() __builtin_amdgcn_sched_barrier(0)
; template <int VAR>
; __device__ __forceinline__ void attn_phase(LAS unsigned char* lds, const AttnP P, int vcu, int G, int wave_s) {
;     ...
;                 if (ND0 == 6) {
;                     KR1(0); KR1(1); KR1(2); KR1(3); SB();
;                     QK1(0, negm); EX2(pc0, 0, w0.x); KR1(4); SB();
;                     QK1(1, negm); EX2(pc0, 2, w0.y); KR1(5); SB();
;                     QK1(2, pn0); EX2(pc0, 4, w0.z); KR1(6); SB();
;                     QK1(3, pn1); EX2(pc0, 6, w0.w); KR1(7); SB();
;                     QK1(4, pn0); EX2(pc0, 8, w1.x); KR1(8); SB();
;                     QK1(5, pn1); EX2(pc0, 10, w1.y); KR1(9); SB();
;                     QK1(6, pn0); EX2(pc0, 12, w1.z); KR1(10); SB();
;                     QK1(7, pn1); EX2(pc0, 14, w1.w); KR1(11); SB();
;                     QK1(8, pn0); EX2(pc1, 0, w2.x); VR1(0); SB();
;                     QK1(9, pn1); EX2(pc1, 2, w2.y); VR1(1); SB();
;                     QK1(10, pn0); EX2(pc1, 4, w2.z); VR1(2); SB();
;                     QK1(11, pn1); EX2(pc1, 6, w2.w); VR1(3); SB();
;                 } else {
;                     KR1(0); KR1(1); KR1(2); KR1(3); SB();
;                     QK1(0, negm); EX2(pc0, 0, w0.x); EX2(pc0, 2, w0.y); KR1(4); SB();
;                     QK1(1, negm); EX2(pc0, 4, w0.z); EX2(pc0, 6, w0.w); KR1(5); SB();
;                     QK1(2, pn0); EX2(pc0, 8, w1.x); EX2(pc0, 10, w1.y); KR1(6); SB();
;                     QK1(3, pn1); EX2(pc0, 12, w1.z); EX2(pc0, 14, w1.w); KR1(7); SB();
;                     QK1(4, pn0); EX2(pc1, 0, w2.x); VR1(0); SB();
;                     QK1(5, pn1); EX2(pc1, 2, w2.y); VR1(1); SB();
;                     QK1(6, pn0); EX2(pc1, 4, w2.z); VR1(2); SB();
;                     QK1(7, pn1); EX2(pc1, 6, w2.w); VR1(3); SB();
;                 }
;                 PV1(0, w0); EX2(pc1, 8, w3.x); VR1(4); SB();
;                 PV1(1, w0); EX2(pc1, 10, w3.y); VR1(5); SB();
;                 PV1(2, w1); EX2(pc1, 12, w3.z); VR1(6); SB();
;                 PV1(3, w1); EX2(pc1, 14, w3.w); VR1(7); SB();
;                 lrun += sacc;
;                 PV1(4, w2); MASK_TILE(pn0, pn1, t + 1); SB();
;                 PV1(5, w2); SB();
;                 PV1(6, w3); SB();
;                 PV1(7, w3); rmn = rowmax32(pn0, pn1); if (!USE_NEGM) rmn -= mref; SB();
.Lmla_p9_go:
	v_exp_f32_e32 v222, v82
	v_exp_f32_e32 v223, v83
	v_add_f32_e32 v164, 0, v222
	v_cvt_pk_bf16_f32 v206, v222, v223
	v_add_f32_e32 v164, v223, v164
	v_exp_f32_e32 v224, v84
	v_exp_f32_e32 v225, v85
	v_add_f32_e32 v164, v224, v164
	v_cvt_pk_bf16_f32 v207, v224, v225
	v_add_f32_e32 v164, v225, v164
	s_waitcnt lgkmcnt(4)
	v_mfma_f32_32x32x16_bf16 v[34:49], v[182:185], v[114:117], v[66:81]
	ds_read_b128 v[198:201], v174 offset:64
	v_exp_f32_e32 v222, v86
	v_exp_f32_e32 v223, v87
	v_add_f32_e32 v164, v222, v164
	v_cvt_pk_bf16_f32 v208, v222, v223
	v_add_f32_e32 v164, v223, v164
	s_waitcnt lgkmcnt(4)
	v_mfma_f32_32x32x16_bf16 v[50:65], v[186:189], v[114:117], v[66:81]
	ds_read_b128 v[182:185], v174 offset:6720
	v_exp_f32_e32 v224, v88
	v_exp_f32_e32 v225, v89
	v_add_f32_e32 v164, v224, v164
	v_cvt_pk_bf16_f32 v209, v224, v225
	v_add_f32_e32 v164, v225, v164
	s_waitcnt lgkmcnt(3)
	v_mfma_f32_32x32x16_bf16 v[34:49], v[190:193], v[118:121], v[34:49]
	ds_read_b128 v[186:189], v174 offset:96
	v_exp_f32_e32 v222, v90
	v_exp_f32_e32 v223, v91
	v_add_f32_e32 v164, v222, v164
	v_cvt_pk_bf16_f32 v210, v222, v223
	v_add_f32_e32 v164, v223, v164
	s_waitcnt lgkmcnt(3)
	v_mfma_f32_32x32x16_bf16 v[50:65], v[194:197], v[118:121], v[50:65]
	ds_read_b128 v[190:193], v174 offset:6752
	v_exp_f32_e32 v224, v92
	v_exp_f32_e32 v225, v93
	v_add_f32_e32 v164, v224, v164
	v_cvt_pk_bf16_f32 v211, v224, v225
	v_add_f32_e32 v164, v225, v164
	s_waitcnt lgkmcnt(3)
	v_mfma_f32_32x32x16_bf16 v[34:49], v[198:201], v[122:125], v[34:49]
	ds_read_b128 v[194:197], v174 offset:128
	v_exp_f32_e32 v222, v94
	v_exp_f32_e32 v223, v95
	v_add_f32_e32 v164, v222, v164
	v_cvt_pk_bf16_f32 v212, v222, v223
	v_add_f32_e32 v164, v223, v164
	s_waitcnt lgkmcnt(3)
	v_mfma_f32_32x32x16_bf16 v[50:65], v[182:185], v[122:125], v[50:65]
	ds_read_b128 v[198:201], v174 offset:6784
	v_exp_f32_e32 v224, v96
	v_exp_f32_e32 v225, v97
	v_add_f32_e32 v164, v224, v164
	v_cvt_pk_bf16_f32 v213, v224, v225
	v_add_f32_e32 v164, v225, v164
	s_waitcnt lgkmcnt(3)
	v_mfma_f32_32x32x16_bf16 v[34:49], v[186:189], v[126:129], v[34:49]
	ds_read_b128 v[182:185], v174 offset:160
	v_exp_f32_e32 v222, v98
	v_exp_f32_e32 v223, v99
	v_add_f32_e32 v164, v222, v164
	v_cvt_pk_bf16_f32 v214, v222, v223
	v_add_f32_e32 v164, v223, v164
	s_waitcnt lgkmcnt(3)
	v_mfma_f32_32x32x16_bf16 v[50:65], v[190:193], v[126:129], v[50:65]
	ds_read_b128 v[186:189], v174 offset:6816
	v_exp_f32_e32 v224, v100
	v_exp_f32_e32 v225, v101
	v_add_f32_e32 v164, v224, v164
	v_cvt_pk_bf16_f32 v215, v224, v225
	v_add_f32_e32 v164, v225, v164
	s_waitcnt lgkmcnt(3)
	v_mfma_f32_32x32x16_bf16 v[34:49], v[194:197], v[130:133], v[34:49]
	ds_read_b128 v[190:193], v228 offset:35840
	v_exp_f32_e32 v222, v102
	v_exp_f32_e32 v223, v103
	v_add_f32_e32 v164, v222, v164
	v_cvt_pk_bf16_f32 v216, v222, v223
	v_add_f32_e32 v164, v223, v164
	s_waitcnt lgkmcnt(3)
	v_mfma_f32_32x32x16_bf16 v[50:65], v[198:201], v[130:133], v[50:65]
	ds_read_b128 v[194:197], v228 offset:40448
	v_exp_f32_e32 v224, v104
	v_exp_f32_e32 v225, v105
	v_add_f32_e32 v164, v224, v164
	v_cvt_pk_bf16_f32 v217, v224, v225
	v_add_f32_e32 v164, v225, v164
	s_waitcnt lgkmcnt(3)
	v_mfma_f32_32x32x16_bf16 v[34:49], v[182:185], v[134:137], v[34:49]
	ds_read_b128 v[198:201], v228 offset:35872
	v_exp_f32_e32 v222, v106
	v_exp_f32_e32 v223, v107
	v_add_f32_e32 v164, v222, v164
	v_cvt_pk_bf16_f32 v218, v222, v223
	v_add_f32_e32 v164, v223, v164
	s_mov_b32 s13, s20
	s_mov_b32 s20, s19
	s_add_i32 s19, s19, 1
	s_cmp_eq_u32 s19, s9
	s_cselect_b32 s19, 0, s19
	s_waitcnt lgkmcnt(3)
	v_mfma_f32_32x32x16_bf16 v[50:65], v[186:189], v[134:137], v[50:65]
	ds_read_b128 v[182:185], v228 offset:40480
	v_exp_f32_e32 v224, v108
	v_exp_f32_e32 v225, v109
	v_add_f32_e32 v164, v224, v164
	v_cvt_pk_bf16_f32 v219, v224, v225
	v_add_f32_e32 v164, v225, v164
	s_waitcnt vmcnt(2)
	ds_write_b128 v172, v[150:153] offset:58368
	v_lshl_add_u32 v222, s19, 17, v178
	global_load_dwordx4 v[150:153], v222, s[52:53]
	s_waitcnt lgkmcnt(4)
	v_mfma_f32_32x32x16_bf16 v[2:17], v[190:193], v[206:209], v[2:17]
	ds_read_b128 v[186:189], v228 offset:35904
	v_exp_f32_e32 v222, v110
	v_exp_f32_e32 v223, v111
	v_add_f32_e32 v164, v222, v164
	v_cvt_pk_bf16_f32 v220, v222, v223
	v_add_f32_e32 v164, v223, v164
	s_and_b64 vcc, exec, s[2:3]
	s_cbranch_vccz .Lmla_p9_nope
	ds_write_b128 v176, v[160:163] offset:58496
	v_lshl_add_u32 v222, s19, 12, v179
	global_load_dwordx4 v[160:163], v222, s[62:63]
.Lmla_p9_nope:
	s_waitcnt lgkmcnt(4)
	v_mfma_f32_32x32x16_bf16 v[18:33], v[194:197], v[206:209], v[18:33]
	ds_read_b128 v[190:193], v228 offset:40512
	v_exp_f32_e32 v224, v112
	v_exp_f32_e32 v225, v113
	v_add_f32_e32 v164, v224, v164
	v_cvt_pk_bf16_f32 v221, v224, v225
	v_add_f32_e32 v164, v225, v164
	v_add_u32_e32 v222, 0xb000, v173
	ds_write_b128 v222, v[202:205] offset:49152
	v_lshl_add_u32 v222, s13, 7, v168
	global_load_dwordx4 v[202:205], v222, s[56:57]
	s_waitcnt lgkmcnt(5)
	v_mfma_f32_32x32x16_bf16 v[2:17], v[198:201], v[210:213], v[2:17]
	ds_read_b128 v[194:197], v228 offset:35936
	v_max3_f32 v224, v34, v35, v36
	v_max3_f32 v225, v50, v51, v52
	v_max3_f32 v224, v224, v37, v38
	v_max3_f32 v225, v225, v53, v54
	s_waitcnt lgkmcnt(5)
	v_mfma_f32_32x32x16_bf16 v[18:33], v[182:185], v[210:213], v[18:33]
	ds_read_b128 v[198:201], v228 offset:40544
	ds_read_b128 v[182:185], v174 offset:22528
	v_max3_f32 v224, v224, v39, v40
	v_max3_f32 v225, v225, v55, v56
	v_max3_f32 v224, v224, v41, v42
	v_max3_f32 v225, v225, v57, v58
	s_waitcnt lgkmcnt(5)
	v_mfma_f32_32x32x16_bf16 v[2:17], v[186:189], v[214:217], v[2:17]
	ds_read_b128 v[186:189], v174 offset:29184
	v_max3_f32 v224, v224, v43, v44
	v_max3_f32 v225, v225, v59, v60
	v_max3_f32 v224, v224, v45, v46
	v_max3_f32 v225, v225, v61, v62
	s_waitcnt lgkmcnt(5)
	v_mfma_f32_32x32x16_bf16 v[18:33], v[190:193], v[214:217], v[18:33]
	ds_read_b128 v[190:193], v174 offset:22560
	v_max3_f32 v224, v224, v47, v48
	v_max3_f32 v225, v225, v63, v64
	v_max3_f32 v224, v224, v49, v65
	v_max_f32_e32 v224, v224, v225
	s_waitcnt lgkmcnt(4)
	v_mfma_f32_32x32x16_bf16 v[2:17], v[194:197], v[218:221], v[2:17]
	ds_read_b128 v[194:197], v174 offset:29216
	v_mov_b32_e32 v225, v224
	v_add_f32_e32 v1, v1, v164
	s_add_i32 s11, s11, 1
	v_permlane32_swap_b32_e32 v224, v225
	s_cmp_eq_u32 s9, s11
	v_max_f32_e32 v167, v224, v225
	v_cmp_lt_f32_e32 vcc, s66, v167
	s_waitcnt lgkmcnt(4)
	v_mfma_f32_32x32x16_bf16 v[18:33], v[198:201], v[218:221], v[18:33]
	s_waitcnt lgkmcnt(6)
	s_barrier

; #define SB() __builtin_amdgcn_sched_barrier(0)
; template <int VAR>
; __device__ __forceinline__ void attn_phase(LAS unsigned char* lds, const AttnP P, int vcu, int G, int wave_s) {
;     ...
;                 if (ND0 == 6) {
;                     KR1(0); KR1(1); KR1(2); KR1(3); SB();
;                     QK1(0, negm); EX2(pc0, 0, w0.x); KR1(4); SB();
;                     QK1(1, negm); EX2(pc0, 2, w0.y); KR1(5); SB();
;                     QK1(2, pn0); EX2(pc0, 4, w0.z); KR1(6); SB();
;                     QK1(3, pn1); EX2(pc0, 6, w0.w); KR1(7); SB();
;                     QK1(4, pn0); EX2(pc0, 8, w1.x); KR1(8); SB();
;                     QK1(5, pn1); EX2(pc0, 10, w1.y); KR1(9); SB();
;                     QK1(6, pn0); EX2(pc0, 12, w1.z); KR1(10); SB();
;                     QK1(7, pn1); EX2(pc0, 14, w1.w); KR1(11); SB();
;                     QK1(8, pn0); EX2(pc1, 0, w2.x); VR1(0); SB();
;                     QK1(9, pn1); EX2(pc1, 2, w2.y); VR1(1); SB();
;                     QK1(10, pn0); EX2(pc1, 4, w2.z); VR1(2); SB();
;                     QK1(11, pn1); EX2(pc1, 6, w2.w); VR1(3); SB();
;                 } else {
;                     KR1(0); KR1(1); KR1(2); KR1(3); SB();
;                     QK1(0, negm); EX2(pc0, 0, w0.x); EX2(pc0, 2, w0.y); KR1(4); SB();
;                     QK1(1, negm); EX2(pc0, 4, w0.z); EX2(pc0, 6, w0.w); KR1(5); SB();
;                     QK1(2, pn0); EX2(pc0, 8, w1.x); EX2(pc0, 10, w1.y); KR1(6); SB();
;                     QK1(3, pn1); EX2(pc0, 12, w1.z); EX2(pc0, 14, w1.w); KR1(7); SB();
;                     QK1(4, pn0); EX2(pc1, 0, w2.x); VR1(0); SB();
;                     QK1(5, pn1); EX2(pc1, 2, w2.y); VR1(1); SB();
;                     QK1(6, pn0); EX2(pc1, 4, w2.z); VR1(2); SB();
;                     QK1(7, pn1); EX2(pc1, 6, w2.w); VR1(3); SB();
;                 }
;                 PV1(0, w0); EX2(pc1, 8, w3.x); VR1(4); SB();
;                 PV1(1, w0); EX2(pc1, 10, w3.y); VR1(5); SB();
;                 PV1(2, w1); EX2(pc1, 12, w3.z); VR1(6); SB();
;                 PV1(3, w1); EX2(pc1, 14, w3.w); VR1(7); SB();
;                 lrun += sacc;
;                 PV1(4, w2); MASK_TILE(pn0, pn1, t + 1); SB();
;                 PV1(5, w2); SB();
;                 PV1(6, w3); SB();
;                 PV1(7, w3); rmn = rowmax32(pn0, pn1); if (!USE_NEGM) rmn -= mref; SB();
.Lmla_p11_go:
	v_exp_f32_e32 v222, v82
	v_exp_f32_e32 v223, v83
	v_add_f32_e32 v164, 0, v222
	v_cvt_pk_bf16_f32 v206, v222, v223
	v_add_f32_e32 v164, v223, v164
	v_exp_f32_e32 v224, v84
	v_exp_f32_e32 v225, v85
	v_add_f32_e32 v164, v224, v164
	v_cvt_pk_bf16_f32 v207, v224, v225
	v_add_f32_e32 v164, v225, v164
	s_waitcnt lgkmcnt(4)
	v_mfma_f32_32x32x16_bf16 v[34:49], v[182:185], v[114:117], v[66:81]
	ds_read_b128 v[198:201], v174 offset:45120
	v_exp_f32_e32 v222, v86
	v_exp_f32_e32 v223, v87
	v_add_f32_e32 v164, v222, v164
	v_cvt_pk_bf16_f32 v208, v222, v223
	v_add_f32_e32 v164, v223, v164
	s_waitcnt lgkmcnt(4)
	v_mfma_f32_32x32x16_bf16 v[50:65], v[186:189], v[114:117], v[66:81]
	ds_read_b128 v[182:185], v174 offset:51776
	v_exp_f32_e32 v224, v88
	v_exp_f32_e32 v225, v89
	v_add_f32_e32 v164, v224, v164
	v_cvt_pk_bf16_f32 v209, v224, v225
	v_add_f32_e32 v164, v225, v164
	s_waitcnt lgkmcnt(3)
	v_mfma_f32_32x32x16_bf16 v[34:49], v[190:193], v[118:121], v[34:49]
	ds_read_b128 v[186:189], v174 offset:45152
	v_exp_f32_e32 v222, v90
	v_exp_f32_e32 v223, v91
	v_add_f32_e32 v164, v222, v164
	v_cvt_pk_bf16_f32 v210, v222, v223
	v_add_f32_e32 v164, v223, v164
	s_waitcnt lgkmcnt(3)
	v_mfma_f32_32x32x16_bf16 v[50:65], v[194:197], v[118:121], v[50:65]
	ds_read_b128 v[190:193], v174 offset:51808
	v_exp_f32_e32 v224, v92
	v_exp_f32_e32 v225, v93
	v_add_f32_e32 v164, v224, v164
	v_cvt_pk_bf16_f32 v211, v224, v225
	v_add_f32_e32 v164, v225, v164
	s_waitcnt lgkmcnt(3)
	v_mfma_f32_32x32x16_bf16 v[34:49], v[198:201], v[122:125], v[34:49]
	ds_read_b128 v[194:197], v174 offset:45184
	v_exp_f32_e32 v222, v94
	v_exp_f32_e32 v223, v95
	v_add_f32_e32 v164, v222, v164
	v_cvt_pk_bf16_f32 v212, v222, v223
	v_add_f32_e32 v164, v223, v164
	s_waitcnt lgkmcnt(3)
	v_mfma_f32_32x32x16_bf16 v[50:65], v[182:185], v[122:125], v[50:65]
	ds_read_b128 v[198:201], v174 offset:51840
	v_exp_f32_e32 v224, v96
	v_exp_f32_e32 v225, v97
	v_add_f32_e32 v164, v224, v164
	v_cvt_pk_bf16_f32 v213, v224, v225
	v_add_f32_e32 v164, v225, v164
	s_waitcnt lgkmcnt(3)
	v_mfma_f32_32x32x16_bf16 v[34:49], v[186:189], v[126:129], v[34:49]
	ds_read_b128 v[182:185], v174 offset:45216
	v_exp_f32_e32 v222, v98
	v_exp_f32_e32 v223, v99
	v_add_f32_e32 v164, v222, v164
	v_cvt_pk_bf16_f32 v214, v222, v223
	v_add_f32_e32 v164, v223, v164
	s_waitcnt lgkmcnt(3)
	v_mfma_f32_32x32x16_bf16 v[50:65], v[190:193], v[126:129], v[50:65]
	ds_read_b128 v[186:189], v174 offset:51872
	v_exp_f32_e32 v224, v100
	v_exp_f32_e32 v225, v101
	v_add_f32_e32 v164, v224, v164
	v_cvt_pk_bf16_f32 v215, v224, v225
	v_add_f32_e32 v164, v225, v164
	s_waitcnt lgkmcnt(3)
	v_mfma_f32_32x32x16_bf16 v[34:49], v[194:197], v[130:133], v[34:49]
	ds_read_b128 v[190:193], v181 offset:49152
	v_exp_f32_e32 v222, v102
	v_exp_f32_e32 v223, v103
	v_add_f32_e32 v164, v222, v164
	v_cvt_pk_bf16_f32 v216, v222, v223
	v_add_f32_e32 v164, v223, v164
	s_waitcnt lgkmcnt(3)
	v_mfma_f32_32x32x16_bf16 v[50:65], v[198:201], v[130:133], v[50:65]
	ds_read_b128 v[194:197], v181 offset:53760
	v_exp_f32_e32 v224, v104
	v_exp_f32_e32 v225, v105
	v_add_f32_e32 v164, v224, v164
	v_cvt_pk_bf16_f32 v217, v224, v225
	v_add_f32_e32 v164, v225, v164
	s_waitcnt lgkmcnt(3)
	v_mfma_f32_32x32x16_bf16 v[34:49], v[182:185], v[134:137], v[34:49]
	ds_read_b128 v[198:201], v181 offset:49184
	v_exp_f32_e32 v222, v106
	v_exp_f32_e32 v223, v107
	v_add_f32_e32 v164, v222, v164
	v_cvt_pk_bf16_f32 v218, v222, v223
	v_add_f32_e32 v164, v223, v164
	s_mov_b32 s13, s20
	s_mov_b32 s20, s19
	s_add_i32 s19, s19, 1
	s_cmp_eq_u32 s19, s9
	s_cselect_b32 s19, 0, s19
	s_waitcnt lgkmcnt(3)
	v_mfma_f32_32x32x16_bf16 v[50:65], v[186:189], v[134:137], v[50:65]
	ds_read_b128 v[182:185], v181 offset:53792
	v_exp_f32_e32 v224, v108
	v_exp_f32_e32 v225, v109
	v_add_f32_e32 v164, v224, v164
	v_cvt_pk_bf16_f32 v219, v224, v225
	v_add_f32_e32 v164, v225, v164
	s_waitcnt vmcnt(2)
	ds_write_b128 v172, v[150:153]
	v_lshl_add_u32 v222, s19, 17, v178
	global_load_dwordx4 v[150:153], v222, s[52:53]
	s_waitcnt lgkmcnt(4)
	v_mfma_f32_32x32x16_bf16 v[2:17], v[190:193], v[206:209], v[2:17]
	ds_read_b128 v[186:189], v181 offset:49216
	v_exp_f32_e32 v222, v110
	v_exp_f32_e32 v223, v111
	v_add_f32_e32 v164, v222, v164
	v_cvt_pk_bf16_f32 v220, v222, v223
	v_add_f32_e32 v164, v223, v164
	s_and_b64 vcc, exec, s[2:3]
	s_cbranch_vccz .Lmla_p11_nope
	ds_write_b128 v176, v[160:163] offset:128
	v_lshl_add_u32 v222, s19, 12, v179
	global_load_dwordx4 v[160:163], v222, s[62:63]
.Lmla_p11_nope:
	s_waitcnt lgkmcnt(4)
	v_mfma_f32_32x32x16_bf16 v[18:33], v[194:197], v[206:209], v[18:33]
	ds_read_b128 v[190:193], v181 offset:53824
	v_exp_f32_e32 v224, v112
	v_exp_f32_e32 v225, v113
	v_add_f32_e32 v164, v224, v164
	v_cvt_pk_bf16_f32 v221, v224, v225
	v_add_f32_e32 v164, v225, v164
	ds_write_b128 v173, v[202:205] offset:35840
	v_lshl_add_u32 v222, s13, 7, v168
	global_load_dwordx4 v[202:205], v222, s[56:57]
	s_waitcnt lgkmcnt(5)
	v_mfma_f32_32x32x16_bf16 v[2:17], v[198:201], v[210:213], v[2:17]
	ds_read_b128 v[194:197], v181 offset:49248
	v_max3_f32 v224, v34, v35, v36
	v_max3_f32 v225, v50, v51, v52
	v_max3_f32 v224, v224, v37, v38
	v_max3_f32 v225, v225, v53, v54
	s_waitcnt lgkmcnt(5)
	v_mfma_f32_32x32x16_bf16 v[18:33], v[182:185], v[210:213], v[18:33]
	ds_read_b128 v[198:201], v181 offset:53856
	ds_read_b128 v[182:185], v229 offset:13312
	v_max3_f32 v224, v224, v39, v40
	v_max3_f32 v225, v225, v55, v56
	v_max3_f32 v224, v224, v41, v42
	v_max3_f32 v225, v225, v57, v58
	s_waitcnt lgkmcnt(5)
	v_mfma_f32_32x32x16_bf16 v[2:17], v[186:189], v[214:217], v[2:17]
	ds_read_b128 v[186:189], v229 offset:19968
	v_max3_f32 v224, v224, v43, v44
	v_max3_f32 v225, v225, v59, v60
	v_max3_f32 v224, v224, v45, v46
	v_max3_f32 v225, v225, v61, v62
	s_waitcnt lgkmcnt(5)
	v_mfma_f32_32x32x16_bf16 v[18:33], v[190:193], v[214:217], v[18:33]
	ds_read_b128 v[190:193], v229 offset:13344
	v_max3_f32 v224, v224, v47, v48
	v_max3_f32 v225, v225, v63, v64
	v_max3_f32 v224, v224, v49, v65
	v_max_f32_e32 v224, v224, v225
	s_waitcnt lgkmcnt(4)
	v_mfma_f32_32x32x16_bf16 v[2:17], v[194:197], v[218:221], v[2:17]
	ds_read_b128 v[194:197], v229 offset:20000
	v_mov_b32_e32 v225, v224
	v_add_f32_e32 v1, v1, v164
	s_add_i32 s11, s11, 1
	v_permlane32_swap_b32_e32 v224, v225
	s_cmp_eq_u32 s9, s11
	v_max_f32_e32 v167, v224, v225
	v_cmp_lt_f32_e32 vcc, s66, v167
	s_waitcnt lgkmcnt(4)
	v_mfma_f32_32x32x16_bf16 v[18:33], v[198:201], v[218:221], v[18:33]
	s_waitcnt lgkmcnt(6)
	s_barrier

; #define SB() __builtin_amdgcn_sched_barrier(0)
; template <int VAR>
; __device__ __forceinline__ void attn_phase(LAS unsigned char* lds, const AttnP P, int vcu, int G, int wave_s) {
;     ...
;                 if (ND0 == 6) {
;                     KR1(0); KR1(1); KR1(2); KR1(3); SB();
;                     QK1(0, negm); EX2(pc0, 0, w0.x); KR1(4); SB();
;                     QK1(1, negm); EX2(pc0, 2, w0.y); KR1(5); SB();
;                     QK1(2, pn0); EX2(pc0, 4, w0.z); KR1(6); SB();
;                     QK1(3, pn1); EX2(pc0, 6, w0.w); KR1(7); SB();
;                     QK1(4, pn0); EX2(pc0, 8, w1.x); KR1(8); SB();
;                     QK1(5, pn1); EX2(pc0, 10, w1.y); KR1(9); SB();
;                     QK1(6, pn0); EX2(pc0, 12, w1.z); KR1(10); SB();
;                     QK1(7, pn1); EX2(pc0, 14, w1.w); KR1(11); SB();
;                     QK1(8, pn0); EX2(pc1, 0, w2.x); VR1(0); SB();
;                     QK1(9, pn1); EX2(pc1, 2, w2.y); VR1(1); SB();
;                     QK1(10, pn0); EX2(pc1, 4, w2.z); VR1(2); SB();
;                     QK1(11, pn1); EX2(pc1, 6, w2.w); VR1(3); SB();
;                 } else {
;                     KR1(0); KR1(1); KR1(2); KR1(3); SB();
;                     QK1(0, negm); EX2(pc0, 0, w0.x); EX2(pc0, 2, w0.y); KR1(4); SB();
;                     QK1(1, negm); EX2(pc0, 4, w0.z); EX2(pc0, 6, w0.w); KR1(5); SB();
;                     QK1(2, pn0); EX2(pc0, 8, w1.x); EX2(pc0, 10, w1.y); KR1(6); SB();
;                     QK1(3, pn1); EX2(pc0, 12, w1.z); EX2(pc0, 14, w1.w); KR1(7); SB();
;                     QK1(4, pn0); EX2(pc1, 0, w2.x); VR1(0); SB();
;                     QK1(5, pn1); EX2(pc1, 2, w2.y); VR1(1); SB();
;                     QK1(6, pn0); EX2(pc1, 4, w2.z); VR1(2); SB();
;                     QK1(7, pn1); EX2(pc1, 6, w2.w); VR1(3); SB();
;                 }
;                 PV1(0, w0); EX2(pc1, 8, w3.x); VR1(4); SB();
;                 PV1(1, w0); EX2(pc1, 10, w3.y); VR1(5); SB();
;                 PV1(2, w1); EX2(pc1, 12, w3.z); VR1(6); SB();
;                 PV1(3, w1); EX2(pc1, 14, w3.w); VR1(7); SB();
;                 lrun += sacc;
;                 PV1(4, w2); MASK_TILE(pn0, pn1, t + 1); SB();
;                 PV1(5, w2); SB();
;                 PV1(6, w3); SB();
;                 PV1(7, w3); rmn = rowmax32(pn0, pn1); if (!USE_NEGM) rmn -= mref; SB();
.Lmla_p13_go:
	v_exp_f32_e32 v222, v82
	v_exp_f32_e32 v223, v83
	v_add_f32_e32 v164, 0, v222
	v_cvt_pk_bf16_f32 v206, v222, v223
	v_add_f32_e32 v164, v223, v164
	v_exp_f32_e32 v224, v84
	v_exp_f32_e32 v225, v85
	v_add_f32_e32 v164, v224, v164
	v_cvt_pk_bf16_f32 v207, v224, v225
	v_add_f32_e32 v164, v225, v164
	s_waitcnt lgkmcnt(4)
	v_mfma_f32_32x32x16_bf16 v[34:49], v[182:185], v[114:117], v[66:81]
	ds_read_b128 v[198:201], v229 offset:26688
	v_exp_f32_e32 v222, v86
	v_exp_f32_e32 v223, v87
	v_add_f32_e32 v164, v222, v164
	v_cvt_pk_bf16_f32 v208, v222, v223
	v_add_f32_e32 v164, v223, v164
	s_waitcnt lgkmcnt(4)
	v_mfma_f32_32x32x16_bf16 v[50:65], v[186:189], v[114:117], v[66:81]
	ds_read_b128 v[182:185], v229 offset:33344
	v_exp_f32_e32 v224, v88
	v_exp_f32_e32 v225, v89
	v_add_f32_e32 v164, v224, v164
	v_cvt_pk_bf16_f32 v209, v224, v225
	v_add_f32_e32 v164, v225, v164
	s_waitcnt lgkmcnt(3)
	v_mfma_f32_32x32x16_bf16 v[34:49], v[190:193], v[118:121], v[34:49]
	ds_read_b128 v[186:189], v229 offset:26720
	v_exp_f32_e32 v222, v90
	v_exp_f32_e32 v223, v91
	v_add_f32_e32 v164, v222, v164
	v_cvt_pk_bf16_f32 v210, v222, v223
	v_add_f32_e32 v164, v223, v164
	s_waitcnt lgkmcnt(3)
	v_mfma_f32_32x32x16_bf16 v[50:65], v[194:197], v[118:121], v[50:65]
	ds_read_b128 v[190:193], v229 offset:33376
	v_exp_f32_e32 v224, v92
	v_exp_f32_e32 v225, v93
	v_add_f32_e32 v164, v224, v164
	v_cvt_pk_bf16_f32 v211, v224, v225
	v_add_f32_e32 v164, v225, v164
	s_waitcnt lgkmcnt(3)
	v_mfma_f32_32x32x16_bf16 v[34:49], v[198:201], v[122:125], v[34:49]
	ds_read_b128 v[194:197], v229 offset:26752
	v_exp_f32_e32 v222, v94
	v_exp_f32_e32 v223, v95
	v_add_f32_e32 v164, v222, v164
	v_cvt_pk_bf16_f32 v212, v222, v223
	v_add_f32_e32 v164, v223, v164
	s_waitcnt lgkmcnt(3)
	v_mfma_f32_32x32x16_bf16 v[50:65], v[182:185], v[122:125], v[50:65]
	ds_read_b128 v[198:201], v229 offset:33408
	v_exp_f32_e32 v224, v96
	v_exp_f32_e32 v225, v97
	v_add_f32_e32 v164, v224, v164
	v_cvt_pk_bf16_f32 v213, v224, v225
	v_add_f32_e32 v164, v225, v164
	s_waitcnt lgkmcnt(3)
	v_mfma_f32_32x32x16_bf16 v[34:49], v[186:189], v[126:129], v[34:49]
	ds_read_b128 v[182:185], v229 offset:26784
	v_exp_f32_e32 v222, v98
	v_exp_f32_e32 v223, v99
	v_add_f32_e32 v164, v222, v164
	v_cvt_pk_bf16_f32 v214, v222, v223
	v_add_f32_e32 v164, v223, v164
	s_waitcnt lgkmcnt(3)
	v_mfma_f32_32x32x16_bf16 v[50:65], v[190:193], v[126:129], v[50:65]
	ds_read_b128 v[186:189], v229 offset:33440
	v_exp_f32_e32 v224, v100
	v_exp_f32_e32 v225, v101
	v_add_f32_e32 v164, v224, v164
	v_cvt_pk_bf16_f32 v215, v224, v225
	v_add_f32_e32 v164, v225, v164
	s_waitcnt lgkmcnt(3)
	v_mfma_f32_32x32x16_bf16 v[34:49], v[194:197], v[130:133], v[34:49]
	ds_read_b128 v[190:193], v228 offset:35840
	v_exp_f32_e32 v222, v102
	v_exp_f32_e32 v223, v103
	v_add_f32_e32 v164, v222, v164
	v_cvt_pk_bf16_f32 v216, v222, v223
	v_add_f32_e32 v164, v223, v164
	s_waitcnt lgkmcnt(3)
	v_mfma_f32_32x32x16_bf16 v[50:65], v[198:201], v[130:133], v[50:65]
	ds_read_b128 v[194:197], v228 offset:40448
	v_exp_f32_e32 v224, v104
	v_exp_f32_e32 v225, v105
	v_add_f32_e32 v164, v224, v164
	v_cvt_pk_bf16_f32 v217, v224, v225
	v_add_f32_e32 v164, v225, v164
	s_waitcnt lgkmcnt(3)
	v_mfma_f32_32x32x16_bf16 v[34:49], v[182:185], v[134:137], v[34:49]
	ds_read_b128 v[198:201], v228 offset:35872
	v_exp_f32_e32 v222, v106
	v_exp_f32_e32 v223, v107
	v_add_f32_e32 v164, v222, v164
	v_cvt_pk_bf16_f32 v218, v222, v223
	v_add_f32_e32 v164, v223, v164
	s_mov_b32 s13, s20
	s_mov_b32 s20, s19
	s_add_i32 s19, s19, 1
	s_cmp_eq_u32 s19, s9
	s_cselect_b32 s19, 0, s19
	s_waitcnt lgkmcnt(3)
	v_mfma_f32_32x32x16_bf16 v[50:65], v[186:189], v[134:137], v[50:65]
	ds_read_b128 v[182:185], v228 offset:40480
	v_exp_f32_e32 v224, v108
	v_exp_f32_e32 v225, v109
	v_add_f32_e32 v164, v224, v164
	v_cvt_pk_bf16_f32 v219, v224, v225
	v_add_f32_e32 v164, v225, v164
	s_waitcnt vmcnt(2)
	ds_write_b128 v172, v[150:153] offset:45056
	v_lshl_add_u32 v222, s19, 17, v178
	global_load_dwordx4 v[150:153], v222, s[52:53]
	s_waitcnt lgkmcnt(4)
	v_mfma_f32_32x32x16_bf16 v[2:17], v[190:193], v[206:209], v[2:17]
	ds_read_b128 v[186:189], v228 offset:35904
	v_exp_f32_e32 v222, v110
	v_exp_f32_e32 v223, v111
	v_add_f32_e32 v164, v222, v164
	v_cvt_pk_bf16_f32 v220, v222, v223
	v_add_f32_e32 v164, v223, v164
	s_and_b64 vcc, exec, s[2:3]
	s_cbranch_vccz .Lmla_p13_nope
	ds_write_b128 v176, v[160:163] offset:45184
	v_lshl_add_u32 v222, s19, 12, v179
	global_load_dwordx4 v[160:163], v222, s[62:63]
.Lmla_p13_nope:
	s_waitcnt lgkmcnt(4)
	v_mfma_f32_32x32x16_bf16 v[18:33], v[194:197], v[206:209], v[18:33]
	ds_read_b128 v[190:193], v228 offset:40512
	v_exp_f32_e32 v224, v112
	v_exp_f32_e32 v225, v113
	v_add_f32_e32 v164, v224, v164
	v_cvt_pk_bf16_f32 v221, v224, v225
	v_add_f32_e32 v164, v225, v164
	v_add_u32_e32 v222, 0xb000, v173
	ds_write_b128 v222, v[202:205] offset:49152
	v_lshl_add_u32 v222, s13, 7, v168
	global_load_dwordx4 v[202:205], v222, s[56:57]
	s_waitcnt lgkmcnt(5)
	v_mfma_f32_32x32x16_bf16 v[2:17], v[198:201], v[210:213], v[2:17]
	ds_read_b128 v[194:197], v228 offset:35936
	v_max3_f32 v224, v34, v35, v36
	v_max3_f32 v225, v50, v51, v52
	v_max3_f32 v224, v224, v37, v38
	v_max3_f32 v225, v225, v53, v54
	s_waitcnt lgkmcnt(5)
	v_mfma_f32_32x32x16_bf16 v[18:33], v[182:185], v[210:213], v[18:33]
	ds_read_b128 v[198:201], v228 offset:40544
	ds_read_b128 v[182:185], v174
	v_max3_f32 v224, v224, v39, v40
	v_max3_f32 v225, v225, v55, v56
	v_max3_f32 v224, v224, v41, v42
	v_max3_f32 v225, v225, v57, v58
	s_waitcnt lgkmcnt(5)
	v_mfma_f32_32x32x16_bf16 v[2:17], v[186:189], v[214:217], v[2:17]
	ds_read_b128 v[186:189], v174 offset:6656
	v_max3_f32 v224, v224, v43, v44
	v_max3_f32 v225, v225, v59, v60
	v_max3_f32 v224, v224, v45, v46
	v_max3_f32 v225, v225, v61, v62
	s_waitcnt lgkmcnt(5)
	v_mfma_f32_32x32x16_bf16 v[18:33], v[190:193], v[214:217], v[18:33]
	ds_read_b128 v[190:193], v174 offset:32
	v_max3_f32 v224, v224, v47, v48
	v_max3_f32 v225, v225, v63, v64
	v_max3_f32 v224, v224, v49, v65
	v_max_f32_e32 v224, v224, v225
	s_waitcnt lgkmcnt(4)
	v_mfma_f32_32x32x16_bf16 v[2:17], v[194:197], v[218:221], v[2:17]
	ds_read_b128 v[194:197], v174 offset:6688
	v_mov_b32_e32 v225, v224
	v_add_f32_e32 v1, v1, v164
	s_add_i32 s11, s11, 1
	v_permlane32_swap_b32_e32 v224, v225
	s_cmp_eq_u32 s9, s11
	v_max_f32_e32 v167, v224, v225
	v_cmp_lt_f32_e32 vcc, s66, v167
	s_waitcnt lgkmcnt(4)
	v_mfma_f32_32x32x16_bf16 v[18:33], v[198:201], v[218:221], v[18:33]
	s_waitcnt lgkmcnt(6)
	s_barrier

; #define SB() __builtin_amdgcn_sched_barrier(0)
; template <int VAR>
; __device__ __forceinline__ void attn_phase(LAS unsigned char* lds, const AttnP P, int vcu, int G, int wave_s) {
;     ...
;                 if (ND0 == 6) {
;                     KR1(0); KR1(1); KR1(2); KR1(3); SB();
;                     QK1(0, negm); EX2(pc0, 0, w0.x); KR1(4); SB();
;                     QK1(1, negm); EX2(pc0, 2, w0.y); KR1(5); SB();
;                     QK1(2, pn0); EX2(pc0, 4, w0.z); KR1(6); SB();
;                     QK1(3, pn1); EX2(pc0, 6, w0.w); KR1(7); SB();
;                     QK1(4, pn0); EX2(pc0, 8, w1.x); KR1(8); SB();
;                     QK1(5, pn1); EX2(pc0, 10, w1.y); KR1(9); SB();
;                     QK1(6, pn0); EX2(pc0, 12, w1.z); KR1(10); SB();
;                     QK1(7, pn1); EX2(pc0, 14, w1.w); KR1(11); SB();
;                     QK1(8, pn0); EX2(pc1, 0, w2.x); VR1(0); SB();
;                     QK1(9, pn1); EX2(pc1, 2, w2.y); VR1(1); SB();
;                     QK1(10, pn0); EX2(pc1, 4, w2.z); VR1(2); SB();
;                     QK1(11, pn1); EX2(pc1, 6, w2.w); VR1(3); SB();
;                 } else {
;                     KR1(0); KR1(1); KR1(2); KR1(3); SB();
;                     QK1(0, negm); EX2(pc0, 0, w0.x); EX2(pc0, 2, w0.y); KR1(4); SB();
;                     QK1(1, negm); EX2(pc0, 4, w0.z); EX2(pc0, 6, w0.w); KR1(5); SB();
;                     QK1(2, pn0); EX2(pc0, 8, w1.x); EX2(pc0, 10, w1.y); KR1(6); SB();
;                     QK1(3, pn1); EX2(pc0, 12, w1.z); EX2(pc0, 14, w1.w); KR1(7); SB();
;                     QK1(4, pn0); EX2(pc1, 0, w2.x); VR1(0); SB();
;                     QK1(5, pn1); EX2(pc1, 2, w2.y); VR1(1); SB();
;                     QK1(6, pn0); EX2(pc1, 4, w2.z); VR1(2); SB();
;                     QK1(7, pn1); EX2(pc1, 6, w2.w); VR1(3); SB();
;                 }
;                 PV1(0, w0); EX2(pc1, 8, w3.x); VR1(4); SB();
;                 PV1(1, w0); EX2(pc1, 10, w3.y); VR1(5); SB();
;                 PV1(2, w1); EX2(pc1, 12, w3.z); VR1(6); SB();
;                 PV1(3, w1); EX2(pc1, 14, w3.w); VR1(7); SB();
;                 lrun += sacc;
;                 PV1(4, w2); MASK_TILE(pn0, pn1, t + 1); SB();
;                 PV1(5, w2); SB();
;                 PV1(6, w3); SB();
;                 PV1(7, w3); rmn = rowmax32(pn0, pn1); if (!USE_NEGM) rmn -= mref; SB();
.Lmla_p15_go:
	v_exp_f32_e32 v222, v82
	v_exp_f32_e32 v223, v83
	v_add_f32_e32 v164, 0, v222
	v_cvt_pk_bf16_f32 v206, v222, v223
	v_add_f32_e32 v164, v223, v164
	v_exp_f32_e32 v224, v84
	v_exp_f32_e32 v225, v85
	v_add_f32_e32 v164, v224, v164
	v_cvt_pk_bf16_f32 v207, v224, v225
	v_add_f32_e32 v164, v225, v164
	s_waitcnt lgkmcnt(4)
	v_mfma_f32_32x32x16_bf16 v[34:49], v[182:185], v[114:117], v[66:81]
	ds_read_b128 v[198:201], v174 offset:22592
	v_exp_f32_e32 v222, v86
	v_exp_f32_e32 v223, v87
	v_add_f32_e32 v164, v222, v164
	v_cvt_pk_bf16_f32 v208, v222, v223
	v_add_f32_e32 v164, v223, v164
	s_waitcnt lgkmcnt(4)
	v_mfma_f32_32x32x16_bf16 v[50:65], v[186:189], v[114:117], v[66:81]
	ds_read_b128 v[182:185], v174 offset:29248
	v_exp_f32_e32 v224, v88
	v_exp_f32_e32 v225, v89
	v_add_f32_e32 v164, v224, v164
	v_cvt_pk_bf16_f32 v209, v224, v225
	v_add_f32_e32 v164, v225, v164
	s_waitcnt lgkmcnt(3)
	v_mfma_f32_32x32x16_bf16 v[34:49], v[190:193], v[118:121], v[34:49]
	ds_read_b128 v[186:189], v174 offset:22624
	v_exp_f32_e32 v222, v90
	v_exp_f32_e32 v223, v91
	v_add_f32_e32 v164, v222, v164
	v_cvt_pk_bf16_f32 v210, v222, v223
	v_add_f32_e32 v164, v223, v164
	s_waitcnt lgkmcnt(3)
	v_mfma_f32_32x32x16_bf16 v[50:65], v[194:197], v[118:121], v[50:65]
	ds_read_b128 v[190:193], v174 offset:29280
	v_exp_f32_e32 v224, v92
	v_exp_f32_e32 v225, v93
	v_add_f32_e32 v164, v224, v164
	v_cvt_pk_bf16_f32 v211, v224, v225
	v_add_f32_e32 v164, v225, v164
	s_waitcnt lgkmcnt(3)
	v_mfma_f32_32x32x16_bf16 v[34:49], v[198:201], v[122:125], v[34:49]
	ds_read_b128 v[194:197], v174 offset:22656
	v_exp_f32_e32 v222, v94
	v_exp_f32_e32 v223, v95
	v_add_f32_e32 v164, v222, v164
	v_cvt_pk_bf16_f32 v212, v222, v223
	v_add_f32_e32 v164, v223, v164
	s_waitcnt lgkmcnt(3)
	v_mfma_f32_32x32x16_bf16 v[50:65], v[182:185], v[122:125], v[50:65]
	ds_read_b128 v[198:201], v174 offset:29312
	v_exp_f32_e32 v224, v96
	v_exp_f32_e32 v225, v97
	v_add_f32_e32 v164, v224, v164
	v_cvt_pk_bf16_f32 v213, v224, v225
	v_add_f32_e32 v164, v225, v164
	s_waitcnt lgkmcnt(3)
	v_mfma_f32_32x32x16_bf16 v[34:49], v[186:189], v[126:129], v[34:49]
	ds_read_b128 v[182:185], v174 offset:22688
	v_exp_f32_e32 v222, v98
	v_exp_f32_e32 v223, v99
	v_add_f32_e32 v164, v222, v164
	v_cvt_pk_bf16_f32 v214, v222, v223
	v_add_f32_e32 v164, v223, v164
	s_waitcnt lgkmcnt(3)
	v_mfma_f32_32x32x16_bf16 v[50:65], v[190:193], v[126:129], v[50:65]
	ds_read_b128 v[186:189], v174 offset:29344
	v_exp_f32_e32 v224, v100
	v_exp_f32_e32 v225, v101
	v_add_f32_e32 v164, v224, v164
	v_cvt_pk_bf16_f32 v215, v224, v225
	v_add_f32_e32 v164, v225, v164
	s_waitcnt lgkmcnt(3)
	v_mfma_f32_32x32x16_bf16 v[34:49], v[194:197], v[130:133], v[34:49]
	ds_read_b128 v[190:193], v181 offset:49152
	v_exp_f32_e32 v222, v102
	v_exp_f32_e32 v223, v103
	v_add_f32_e32 v164, v222, v164
	v_cvt_pk_bf16_f32 v216, v222, v223
	v_add_f32_e32 v164, v223, v164
	s_waitcnt lgkmcnt(3)
	v_mfma_f32_32x32x16_bf16 v[50:65], v[198:201], v[130:133], v[50:65]
	ds_read_b128 v[194:197], v181 offset:53760
	v_exp_f32_e32 v224, v104
	v_exp_f32_e32 v225, v105
	v_add_f32_e32 v164, v224, v164
	v_cvt_pk_bf16_f32 v217, v224, v225
	v_add_f32_e32 v164, v225, v164
	s_waitcnt lgkmcnt(3)
	v_mfma_f32_32x32x16_bf16 v[34:49], v[182:185], v[134:137], v[34:49]
	ds_read_b128 v[198:201], v181 offset:49184
	v_exp_f32_e32 v222, v106
	v_exp_f32_e32 v223, v107
	v_add_f32_e32 v164, v222, v164
	v_cvt_pk_bf16_f32 v218, v222, v223
	v_add_f32_e32 v164, v223, v164
	s_mov_b32 s13, s20
	s_mov_b32 s20, s19
	s_add_i32 s19, s19, 1
	s_cmp_eq_u32 s19, s9
	s_cselect_b32 s19, 0, s19
	s_waitcnt lgkmcnt(3)
	v_mfma_f32_32x32x16_bf16 v[50:65], v[186:189], v[134:137], v[50:65]
	ds_read_b128 v[182:185], v181 offset:53792
	v_exp_f32_e32 v224, v108
	v_exp_f32_e32 v225, v109
	v_add_f32_e32 v164, v224, v164
	v_cvt_pk_bf16_f32 v219, v224, v225
	v_add_f32_e32 v164, v225, v164
	s_waitcnt vmcnt(2)
	v_add_u32_e32 v222, 0xb000, v172
	ds_write_b128 v222, v[150:153] offset:26624
	v_lshl_add_u32 v222, s19, 17, v178
	global_load_dwordx4 v[150:153], v222, s[52:53]
	s_waitcnt lgkmcnt(4)
	v_mfma_f32_32x32x16_bf16 v[2:17], v[190:193], v[206:209], v[2:17]
	ds_read_b128 v[186:189], v181 offset:49216
	v_exp_f32_e32 v222, v110
	v_exp_f32_e32 v223, v111
	v_add_f32_e32 v164, v222, v164
	v_cvt_pk_bf16_f32 v220, v222, v223
	v_add_f32_e32 v164, v223, v164
	s_and_b64 vcc, exec, s[2:3]
	s_cbranch_vccz .Lmla_p15_nope
	v_add_u32_e32 v222, 0xb000, v176
	ds_write_b128 v222, v[160:163] offset:26752
	v_lshl_add_u32 v222, s19, 12, v179
	global_load_dwordx4 v[160:163], v222, s[62:63]
.Lmla_p15_nope:
	s_waitcnt lgkmcnt(4)
	v_mfma_f32_32x32x16_bf16 v[18:33], v[194:197], v[206:209], v[18:33]
	ds_read_b128 v[190:193], v181 offset:53824
	v_exp_f32_e32 v224, v112
	v_exp_f32_e32 v225, v113
	v_add_f32_e32 v164, v224, v164
	v_cvt_pk_bf16_f32 v221, v224, v225
	v_add_f32_e32 v164, v225, v164
	ds_write_b128 v173, v[202:205] offset:35840
	v_lshl_add_u32 v222, s13, 7, v168
	global_load_dwordx4 v[202:205], v222, s[56:57]
	s_waitcnt lgkmcnt(5)
	v_mfma_f32_32x32x16_bf16 v[2:17], v[198:201], v[210:213], v[2:17]
	ds_read_b128 v[194:197], v181 offset:49248
	v_max3_f32 v224, v34, v35, v36
	v_max3_f32 v225, v50, v51, v52
	v_max3_f32 v224, v224, v37, v38
	v_max3_f32 v225, v225, v53, v54
	s_waitcnt lgkmcnt(5)
	v_mfma_f32_32x32x16_bf16 v[18:33], v[182:185], v[210:213], v[18:33]
	ds_read_b128 v[198:201], v181 offset:53856
	ds_read_b128 v[182:185], v174 offset:45056
	v_max3_f32 v224, v224, v39, v40
	v_max3_f32 v225, v225, v55, v56
	v_max3_f32 v224, v224, v41, v42
	v_max3_f32 v225, v225, v57, v58
	s_waitcnt lgkmcnt(5)
	v_mfma_f32_32x32x16_bf16 v[2:17], v[186:189], v[214:217], v[2:17]
	ds_read_b128 v[186:189], v174 offset:51712
	v_max3_f32 v224, v224, v43, v44
	v_max3_f32 v225, v225, v59, v60
	v_max3_f32 v224, v224, v45, v46
	v_max3_f32 v225, v225, v61, v62
	s_waitcnt lgkmcnt(5)
	v_mfma_f32_32x32x16_bf16 v[18:33], v[190:193], v[214:217], v[18:33]
	ds_read_b128 v[190:193], v174 offset:45088
	v_max3_f32 v224, v224, v47, v48
	v_max3_f32 v225, v225, v63, v64
	v_max3_f32 v224, v224, v49, v65
	v_max_f32_e32 v224, v224, v225
	s_waitcnt lgkmcnt(4)
	v_mfma_f32_32x32x16_bf16 v[2:17], v[194:197], v[218:221], v[2:17]
	ds_read_b128 v[194:197], v174 offset:51744
	v_mov_b32_e32 v225, v224
	v_add_f32_e32 v1, v1, v164
	s_add_i32 s11, s11, 1
	v_permlane32_swap_b32_e32 v224, v225
	s_cmp_eq_u32 s9, s11
	v_max_f32_e32 v167, v224, v225
	v_cmp_lt_f32_e32 vcc, s66, v167
	s_waitcnt lgkmcnt(4)
	v_mfma_f32_32x32x16_bf16 v[18:33], v[198:201], v[218:221], v[18:33]
	s_waitcnt lgkmcnt(6)
	s_barrier

; #define SB() __builtin_amdgcn_sched_barrier(0)
; template <int VAR>
; __device__ __forceinline__ void attn_phase(LAS unsigned char* lds, const AttnP P, int vcu, int G, int wave_s) {
;     ...
;                 if (ND0 == 6) {
;                     KR1(0); KR1(1); KR1(2); KR1(3); SB();
;                     QK1(0, negm); EX2(pc0, 0, w0.x); KR1(4); SB();
;                     QK1(1, negm); EX2(pc0, 2, w0.y); KR1(5); SB();
;                     QK1(2, pn0); EX2(pc0, 4, w0.z); KR1(6); SB();
;                     QK1(3, pn1); EX2(pc0, 6, w0.w); KR1(7); SB();
;                     QK1(4, pn0); EX2(pc0, 8, w1.x); KR1(8); SB();
;                     QK1(5, pn1); EX2(pc0, 10, w1.y); KR1(9); SB();
;                     QK1(6, pn0); EX2(pc0, 12, w1.z); KR1(10); SB();
;                     QK1(7, pn1); EX2(pc0, 14, w1.w); KR1(11); SB();
;                     QK1(8, pn0); EX2(pc1, 0, w2.x); VR1(0); SB();
;                     QK1(9, pn1); EX2(pc1, 2, w2.y); VR1(1); SB();
;                     QK1(10, pn0); EX2(pc1, 4, w2.z); VR1(2); SB();
;                     QK1(11, pn1); EX2(pc1, 6, w2.w); VR1(3); SB();
;                 } else {
;                     KR1(0); KR1(1); KR1(2); KR1(3); SB();
;                     QK1(0, negm); EX2(pc0, 0, w0.x); EX2(pc0, 2, w0.y); KR1(4); SB();
;                     QK1(1, negm); EX2(pc0, 4, w0.z); EX2(pc0, 6, w0.w); KR1(5); SB();
;                     QK1(2, pn0); EX2(pc0, 8, w1.x); EX2(pc0, 10, w1.y); KR1(6); SB();
;                     QK1(3, pn1); EX2(pc0, 12, w1.z); EX2(pc0, 14, w1.w); KR1(7); SB();
;                     QK1(4, pn0); EX2(pc1, 0, w2.x); VR1(0); SB();
;                     QK1(5, pn1); EX2(pc1, 2, w2.y); VR1(1); SB();
;                     QK1(6, pn0); EX2(pc1, 4, w2.z); VR1(2); SB();
;                     QK1(7, pn1); EX2(pc1, 6, w2.w); VR1(3); SB();
;                 }
;                 PV1(0, w0); EX2(pc1, 8, w3.x); VR1(4); SB();
;                 PV1(1, w0); EX2(pc1, 10, w3.y); VR1(5); SB();
;                 PV1(2, w1); EX2(pc1, 12, w3.z); VR1(6); SB();
;                 PV1(3, w1); EX2(pc1, 14, w3.w); VR1(7); SB();
;                 lrun += sacc;
;                 PV1(4, w2); MASK_TILE(pn0, pn1, t + 1); SB();
;                 PV1(5, w2); SB();
;                 PV1(6, w3); SB();
;                 PV1(7, w3); rmn = rowmax32(pn0, pn1); if (!USE_NEGM) rmn -= mref; SB();
.Lmla_p17_go:
	v_exp_f32_e32 v222, v82
	v_exp_f32_e32 v223, v83
	v_add_f32_e32 v164, 0, v222
	v_cvt_pk_bf16_f32 v206, v222, v223
	v_add_f32_e32 v164, v223, v164
	v_exp_f32_e32 v224, v84
	v_exp_f32_e32 v225, v85
	v_add_f32_e32 v164, v224, v164
	v_cvt_pk_bf16_f32 v207, v224, v225
	v_add_f32_e32 v164, v225, v164
	s_waitcnt lgkmcnt(4)
	v_mfma_f32_32x32x16_bf16 v[34:49], v[182:185], v[114:117], v[66:81]
	ds_read_b128 v[198:201], v229 offset:13376
	v_exp_f32_e32 v222, v86
	v_exp_f32_e32 v223, v87
	v_add_f32_e32 v164, v222, v164
	v_cvt_pk_bf16_f32 v208, v222, v223
	v_add_f32_e32 v164, v223, v164
	s_waitcnt lgkmcnt(4)
	v_mfma_f32_32x32x16_bf16 v[50:65], v[186:189], v[114:117], v[66:81]
	ds_read_b128 v[182:185], v229 offset:20032
	v_exp_f32_e32 v224, v88
	v_exp_f32_e32 v225, v89
	v_add_f32_e32 v164, v224, v164
	v_cvt_pk_bf16_f32 v209, v224, v225
	v_add_f32_e32 v164, v225, v164
	s_waitcnt lgkmcnt(3)
	v_mfma_f32_32x32x16_bf16 v[34:49], v[190:193], v[118:121], v[34:49]
	ds_read_b128 v[186:189], v229 offset:13408
	v_exp_f32_e32 v222, v90
	v_exp_f32_e32 v223, v91
	v_add_f32_e32 v164, v222, v164
	v_cvt_pk_bf16_f32 v210, v222, v223
	v_add_f32_e32 v164, v223, v164
	s_waitcnt lgkmcnt(3)
	v_mfma_f32_32x32x16_bf16 v[50:65], v[194:197], v[118:121], v[50:65]
	ds_read_b128 v[190:193], v229 offset:20064
	v_exp_f32_e32 v224, v92
	v_exp_f32_e32 v225, v93
	v_add_f32_e32 v164, v224, v164
	v_cvt_pk_bf16_f32 v211, v224, v225
	v_add_f32_e32 v164, v225, v164
	s_waitcnt lgkmcnt(3)
	v_mfma_f32_32x32x16_bf16 v[34:49], v[198:201], v[122:125], v[34:49]
	ds_read_b128 v[194:197], v229 offset:13440
	v_exp_f32_e32 v222, v94
	v_exp_f32_e32 v223, v95
	v_add_f32_e32 v164, v222, v164
	v_cvt_pk_bf16_f32 v212, v222, v223
	v_add_f32_e32 v164, v223, v164
	s_waitcnt lgkmcnt(3)
	v_mfma_f32_32x32x16_bf16 v[50:65], v[182:185], v[122:125], v[50:65]
	ds_read_b128 v[198:201], v229 offset:20096
	v_exp_f32_e32 v224, v96
	v_exp_f32_e32 v225, v97
	v_add_f32_e32 v164, v224, v164
	v_cvt_pk_bf16_f32 v213, v224, v225
	v_add_f32_e32 v164, v225, v164
	s_waitcnt lgkmcnt(3)
	v_mfma_f32_32x32x16_bf16 v[34:49], v[186:189], v[126:129], v[34:49]
	ds_read_b128 v[182:185], v229 offset:13472
	v_exp_f32_e32 v222, v98
	v_exp_f32_e32 v223, v99
	v_add_f32_e32 v164, v222, v164
	v_cvt_pk_bf16_f32 v214, v222, v223
	v_add_f32_e32 v164, v223, v164
	s_waitcnt lgkmcnt(3)
	v_mfma_f32_32x32x16_bf16 v[50:65], v[190:193], v[126:129], v[50:65]
	ds_read_b128 v[186:189], v229 offset:20128
	v_exp_f32_e32 v224, v100
	v_exp_f32_e32 v225, v101
	v_add_f32_e32 v164, v224, v164
	v_cvt_pk_bf16_f32 v215, v224, v225
	v_add_f32_e32 v164, v225, v164
	s_waitcnt lgkmcnt(3)
	v_mfma_f32_32x32x16_bf16 v[34:49], v[194:197], v[130:133], v[34:49]
	ds_read_b128 v[190:193], v228 offset:35840
	v_exp_f32_e32 v222, v102
	v_exp_f32_e32 v223, v103
	v_add_f32_e32 v164, v222, v164
	v_cvt_pk_bf16_f32 v216, v222, v223
	v_add_f32_e32 v164, v223, v164
	s_waitcnt lgkmcnt(3)
	v_mfma_f32_32x32x16_bf16 v[50:65], v[198:201], v[130:133], v[50:65]
	ds_read_b128 v[194:197], v228 offset:40448
	v_exp_f32_e32 v224, v104
	v_exp_f32_e32 v225, v105
	v_add_f32_e32 v164, v224, v164
	v_cvt_pk_bf16_f32 v217, v224, v225
	v_add_f32_e32 v164, v225, v164
	s_waitcnt lgkmcnt(3)
	v_mfma_f32_32x32x16_bf16 v[34:49], v[182:185], v[134:137], v[34:49]
	ds_read_b128 v[198:201], v228 offset:35872
	v_exp_f32_e32 v222, v106
	v_exp_f32_e32 v223, v107
	v_add_f32_e32 v164, v222, v164
	v_cvt_pk_bf16_f32 v218, v222, v223
	v_add_f32_e32 v164, v223, v164
	s_mov_b32 s13, s20
	s_mov_b32 s20, s19
	s_add_i32 s19, s19, 1
	s_cmp_eq_u32 s19, s9
	s_cselect_b32 s19, 0, s19
	s_waitcnt lgkmcnt(3)
	v_mfma_f32_32x32x16_bf16 v[50:65], v[186:189], v[134:137], v[50:65]
	ds_read_b128 v[182:185], v228 offset:40480
	v_exp_f32_e32 v224, v108
	v_exp_f32_e32 v225, v109
	v_add_f32_e32 v164, v224, v164
	v_cvt_pk_bf16_f32 v219, v224, v225
	v_add_f32_e32 v164, v225, v164
	s_waitcnt vmcnt(2)
	ds_write_b128 v172, v[150:153] offset:22528
	v_lshl_add_u32 v222, s19, 17, v178
	global_load_dwordx4 v[150:153], v222, s[52:53]
	s_waitcnt lgkmcnt(4)
	v_mfma_f32_32x32x16_bf16 v[2:17], v[190:193], v[206:209], v[2:17]
	ds_read_b128 v[186:189], v228 offset:35904
	v_exp_f32_e32 v222, v110
	v_exp_f32_e32 v223, v111
	v_add_f32_e32 v164, v222, v164
	v_cvt_pk_bf16_f32 v220, v222, v223
	v_add_f32_e32 v164, v223, v164
	s_and_b64 vcc, exec, s[2:3]
	s_cbranch_vccz .Lmla_p17_nope
	ds_write_b128 v176, v[160:163] offset:22656
	v_lshl_add_u32 v222, s19, 12, v179
	global_load_dwordx4 v[160:163], v222, s[62:63]
.Lmla_p17_nope:
	s_waitcnt lgkmcnt(4)
	v_mfma_f32_32x32x16_bf16 v[18:33], v[194:197], v[206:209], v[18:33]
	ds_read_b128 v[190:193], v228 offset:40512
	v_exp_f32_e32 v224, v112
	v_exp_f32_e32 v225, v113
	v_add_f32_e32 v164, v224, v164
	v_cvt_pk_bf16_f32 v221, v224, v225
	v_add_f32_e32 v164, v225, v164
	v_add_u32_e32 v222, 0xb000, v173
	ds_write_b128 v222, v[202:205] offset:49152
	v_lshl_add_u32 v222, s13, 7, v168
	global_load_dwordx4 v[202:205], v222, s[56:57]
	s_waitcnt lgkmcnt(5)
	v_mfma_f32_32x32x16_bf16 v[2:17], v[198:201], v[210:213], v[2:17]
	ds_read_b128 v[194:197], v228 offset:35936
	v_max3_f32 v224, v34, v35, v36
	v_max3_f32 v225, v50, v51, v52
	v_max3_f32 v224, v224, v37, v38
	v_max3_f32 v225, v225, v53, v54
	s_waitcnt lgkmcnt(5)
	v_mfma_f32_32x32x16_bf16 v[18:33], v[182:185], v[210:213], v[18:33]
	ds_read_b128 v[198:201], v228 offset:40544
	ds_read_b128 v[182:185], v229 offset:26624
	v_max3_f32 v224, v224, v39, v40
	v_max3_f32 v225, v225, v55, v56
	v_max3_f32 v224, v224, v41, v42
	v_max3_f32 v225, v225, v57, v58
	s_waitcnt lgkmcnt(5)
	v_mfma_f32_32x32x16_bf16 v[2:17], v[186:189], v[214:217], v[2:17]
	ds_read_b128 v[186:189], v229 offset:33280
	v_max3_f32 v224, v224, v43, v44
	v_max3_f32 v225, v225, v59, v60
	v_max3_f32 v224, v224, v45, v46
	v_max3_f32 v225, v225, v61, v62
	s_waitcnt lgkmcnt(5)
	v_mfma_f32_32x32x16_bf16 v[18:33], v[190:193], v[214:217], v[18:33]
	ds_read_b128 v[190:193], v229 offset:26656
	v_max3_f32 v224, v224, v47, v48
	v_max3_f32 v225, v225, v63, v64
	v_max3_f32 v224, v224, v49, v65
	v_max_f32_e32 v224, v224, v225
	s_waitcnt lgkmcnt(4)
	v_mfma_f32_32x32x16_bf16 v[2:17], v[194:197], v[218:221], v[2:17]
	ds_read_b128 v[194:197], v229 offset:33312
	v_mov_b32_e32 v225, v224
	v_add_f32_e32 v1, v1, v164
	s_add_i32 s11, s11, 1
	v_permlane32_swap_b32_e32 v224, v225
	s_cmp_eq_u32 s9, s11
	v_max_f32_e32 v167, v224, v225
	v_cmp_lt_f32_e32 vcc, s66, v167
	s_waitcnt lgkmcnt(4)
	v_mfma_f32_32x32x16_bf16 v[18:33], v[198:201], v[218:221], v[18:33]
	s_waitcnt lgkmcnt(6)
	s_barrier

; #define SB() __builtin_amdgcn_sched_barrier(0)
; template <int VAR>
; __device__ __forceinline__ void attn_phase(LAS unsigned char* lds, const AttnP P, int vcu, int G, int wave_s) {
;     ...
;                 if (ND0 == 6) {
;                     KR1(0); KR1(1); KR1(2); KR1(3); SB();
;                     QK1(0, negm); EX2(pc0, 0, w0.x); KR1(4); SB();
;                     QK1(1, negm); EX2(pc0, 2, w0.y); KR1(5); SB();
;                     QK1(2, pn0); EX2(pc0, 4, w0.z); KR1(6); SB();
;                     QK1(3, pn1); EX2(pc0, 6, w0.w); KR1(7); SB();
;                     QK1(4, pn0); EX2(pc0, 8, w1.x); KR1(8); SB();
;                     QK1(5, pn1); EX2(pc0, 10, w1.y); KR1(9); SB();
;                     QK1(6, pn0); EX2(pc0, 12, w1.z); KR1(10); SB();
;                     QK1(7, pn1); EX2(pc0, 14, w1.w); KR1(11); SB();
;                     QK1(8, pn0); EX2(pc1, 0, w2.x); VR1(0); SB();
;                     QK1(9, pn1); EX2(pc1, 2, w2.y); VR1(1); SB();
;                     QK1(10, pn0); EX2(pc1, 4, w2.z); VR1(2); SB();
;                     QK1(11, pn1); EX2(pc1, 6, w2.w); VR1(3); SB();
;                 } else {
;                     KR1(0); KR1(1); KR1(2); KR1(3); SB();
;                     QK1(0, negm); EX2(pc0, 0, w0.x); EX2(pc0, 2, w0.y); KR1(4); SB();
;                     QK1(1, negm); EX2(pc0, 4, w0.z); EX2(pc0, 6, w0.w); KR1(5); SB();
;                     QK1(2, pn0); EX2(pc0, 8, w1.x); EX2(pc0, 10, w1.y); KR1(6); SB();
;                     QK1(3, pn1); EX2(pc0, 12, w1.z); EX2(pc0, 14, w1.w); KR1(7); SB();
;                     QK1(4, pn0); EX2(pc1, 0, w2.x); VR1(0); SB();
;                     QK1(5, pn1); EX2(pc1, 2, w2.y); VR1(1); SB();
;                     QK1(6, pn0); EX2(pc1, 4, w2.z); VR1(2); SB();
;                     QK1(7, pn1); EX2(pc1, 6, w2.w); VR1(3); SB();
;                 }
;                 PV1(0, w0); EX2(pc1, 8, w3.x); VR1(4); SB();
;                 PV1(1, w0); EX2(pc1, 10, w3.y); VR1(5); SB();
;                 PV1(2, w1); EX2(pc1, 12, w3.z); VR1(6); SB();
;                 PV1(3, w1); EX2(pc1, 14, w3.w); VR1(7); SB();
;                 lrun += sacc;
;                 PV1(4, w2); MASK_TILE(pn0, pn1, t + 1); SB();
;                 PV1(5, w2); SB();
;                 PV1(6, w3); SB();
;                 PV1(7, w3); rmn = rowmax32(pn0, pn1); if (!USE_NEGM) rmn -= mref; SB();
.Lmla_p19_go:
	v_exp_f32_e32 v222, v82
	v_exp_f32_e32 v223, v83
	v_add_f32_e32 v164, 0, v222
	v_cvt_pk_bf16_f32 v206, v222, v223
	v_add_f32_e32 v164, v223, v164
	v_exp_f32_e32 v224, v84
	v_exp_f32_e32 v225, v85
	v_add_f32_e32 v164, v224, v164
	v_cvt_pk_bf16_f32 v207, v224, v225
	v_add_f32_e32 v164, v225, v164
	s_waitcnt lgkmcnt(4)
	v_mfma_f32_32x32x16_bf16 v[34:49], v[182:185], v[114:117], v[66:81]
	ds_read_b128 v[198:201], v174 offset:64
	v_exp_f32_e32 v222, v86
	v_exp_f32_e32 v223, v87
	v_add_f32_e32 v164, v222, v164
	v_cvt_pk_bf16_f32 v208, v222, v223
	v_add_f32_e32 v164, v223, v164
	s_waitcnt lgkmcnt(4)
	v_mfma_f32_32x32x16_bf16 v[50:65], v[186:189], v[114:117], v[66:81]
	ds_read_b128 v[182:185], v174 offset:6720
	v_exp_f32_e32 v224, v88
	v_exp_f32_e32 v225, v89
	v_add_f32_e32 v164, v224, v164
	v_cvt_pk_bf16_f32 v209, v224, v225
	v_add_f32_e32 v164, v225, v164
	s_waitcnt lgkmcnt(3)
	v_mfma_f32_32x32x16_bf16 v[34:49], v[190:193], v[118:121], v[34:49]
	ds_read_b128 v[186:189], v174 offset:96
	v_exp_f32_e32 v222, v90
	v_exp_f32_e32 v223, v91
	v_add_f32_e32 v164, v222, v164
	v_cvt_pk_bf16_f32 v210, v222, v223
	v_add_f32_e32 v164, v223, v164
	s_waitcnt lgkmcnt(3)
	v_mfma_f32_32x32x16_bf16 v[50:65], v[194:197], v[118:121], v[50:65]
	ds_read_b128 v[190:193], v174 offset:6752
	v_exp_f32_e32 v224, v92
	v_exp_f32_e32 v225, v93
	v_add_f32_e32 v164, v224, v164
	v_cvt_pk_bf16_f32 v211, v224, v225
	v_add_f32_e32 v164, v225, v164
	s_waitcnt lgkmcnt(3)
	v_mfma_f32_32x32x16_bf16 v[34:49], v[198:201], v[122:125], v[34:49]
	ds_read_b128 v[194:197], v174 offset:128
	v_exp_f32_e32 v222, v94
	v_exp_f32_e32 v223, v95
	v_add_f32_e32 v164, v222, v164
	v_cvt_pk_bf16_f32 v212, v222, v223
	v_add_f32_e32 v164, v223, v164
	s_waitcnt lgkmcnt(3)
	v_mfma_f32_32x32x16_bf16 v[50:65], v[182:185], v[122:125], v[50:65]
	ds_read_b128 v[198:201], v174 offset:6784
	v_exp_f32_e32 v224, v96
	v_exp_f32_e32 v225, v97
	v_add_f32_e32 v164, v224, v164
	v_cvt_pk_bf16_f32 v213, v224, v225
	v_add_f32_e32 v164, v225, v164
	s_waitcnt lgkmcnt(3)
	v_mfma_f32_32x32x16_bf16 v[34:49], v[186:189], v[126:129], v[34:49]
	ds_read_b128 v[182:185], v174 offset:160
	v_exp_f32_e32 v222, v98
	v_exp_f32_e32 v223, v99
	v_add_f32_e32 v164, v222, v164
	v_cvt_pk_bf16_f32 v214, v222, v223
	v_add_f32_e32 v164, v223, v164
	s_waitcnt lgkmcnt(3)
	v_mfma_f32_32x32x16_bf16 v[50:65], v[190:193], v[126:129], v[50:65]
	ds_read_b128 v[186:189], v174 offset:6816
	v_exp_f32_e32 v224, v100
	v_exp_f32_e32 v225, v101
	v_add_f32_e32 v164, v224, v164
	v_cvt_pk_bf16_f32 v215, v224, v225
	v_add_f32_e32 v164, v225, v164
	s_waitcnt lgkmcnt(3)
	v_mfma_f32_32x32x16_bf16 v[34:49], v[194:197], v[130:133], v[34:49]
	ds_read_b128 v[190:193], v181 offset:49152
	v_exp_f32_e32 v222, v102
	v_exp_f32_e32 v223, v103
	v_add_f32_e32 v164, v222, v164
	v_cvt_pk_bf16_f32 v216, v222, v223
	v_add_f32_e32 v164, v223, v164
	s_waitcnt lgkmcnt(3)
	v_mfma_f32_32x32x16_bf16 v[50:65], v[198:201], v[130:133], v[50:65]
	ds_read_b128 v[194:197], v181 offset:53760
	v_exp_f32_e32 v224, v104
	v_exp_f32_e32 v225, v105
	v_add_f32_e32 v164, v224, v164
	v_cvt_pk_bf16_f32 v217, v224, v225
	v_add_f32_e32 v164, v225, v164
	s_waitcnt lgkmcnt(3)
	v_mfma_f32_32x32x16_bf16 v[34:49], v[182:185], v[134:137], v[34:49]
	ds_read_b128 v[198:201], v181 offset:49184
	v_exp_f32_e32 v222, v106
	v_exp_f32_e32 v223, v107
	v_add_f32_e32 v164, v222, v164
	v_cvt_pk_bf16_f32 v218, v222, v223
	v_add_f32_e32 v164, v223, v164
	s_mov_b32 s13, s20
	s_mov_b32 s20, s19
	s_add_i32 s19, s19, 1
	s_cmp_eq_u32 s19, s9
	s_cselect_b32 s19, 0, s19
	s_waitcnt lgkmcnt(3)
	v_mfma_f32_32x32x16_bf16 v[50:65], v[186:189], v[134:137], v[50:65]
	ds_read_b128 v[182:185], v181 offset:53792
	v_exp_f32_e32 v224, v108
	v_exp_f32_e32 v225, v109
	v_add_f32_e32 v164, v224, v164
	v_cvt_pk_bf16_f32 v219, v224, v225
	v_add_f32_e32 v164, v225, v164
	s_waitcnt vmcnt(2)
	ds_write_b128 v172, v[150:153] offset:58368
	v_lshl_add_u32 v222, s19, 17, v178
	global_load_dwordx4 v[150:153], v222, s[52:53]
	s_waitcnt lgkmcnt(4)
	v_mfma_f32_32x32x16_bf16 v[2:17], v[190:193], v[206:209], v[2:17]
	ds_read_b128 v[186:189], v181 offset:49216
	v_exp_f32_e32 v222, v110
	v_exp_f32_e32 v223, v111
	v_add_f32_e32 v164, v222, v164
	v_cvt_pk_bf16_f32 v220, v222, v223
	v_add_f32_e32 v164, v223, v164
	s_and_b64 vcc, exec, s[2:3]
	s_cbranch_vccz .Lmla_p19_nope
	ds_write_b128 v176, v[160:163] offset:58496
	v_lshl_add_u32 v222, s19, 12, v179
	global_load_dwordx4 v[160:163], v222, s[62:63]
.Lmla_p19_nope:
	s_waitcnt lgkmcnt(4)
	v_mfma_f32_32x32x16_bf16 v[18:33], v[194:197], v[206:209], v[18:33]
	ds_read_b128 v[190:193], v181 offset:53824
	v_exp_f32_e32 v224, v112
	v_exp_f32_e32 v225, v113
	v_add_f32_e32 v164, v224, v164
	v_cvt_pk_bf16_f32 v221, v224, v225
	v_add_f32_e32 v164, v225, v164
	ds_write_b128 v173, v[202:205] offset:35840
	v_lshl_add_u32 v222, s13, 7, v168
	global_load_dwordx4 v[202:205], v222, s[56:57]
	s_waitcnt lgkmcnt(5)
	v_mfma_f32_32x32x16_bf16 v[2:17], v[198:201], v[210:213], v[2:17]
	ds_read_b128 v[194:197], v181 offset:49248
	v_max3_f32 v224, v34, v35, v36
	v_max3_f32 v225, v50, v51, v52
	v_max3_f32 v224, v224, v37, v38
	v_max3_f32 v225, v225, v53, v54
	s_waitcnt lgkmcnt(5)
	v_mfma_f32_32x32x16_bf16 v[18:33], v[182:185], v[210:213], v[18:33]
	ds_read_b128 v[198:201], v181 offset:53856
	ds_read_b128 v[182:185], v174 offset:22528
	v_max3_f32 v224, v224, v39, v40
	v_max3_f32 v225, v225, v55, v56
	v_max3_f32 v224, v224, v41, v42
	v_max3_f32 v225, v225, v57, v58
	s_waitcnt lgkmcnt(5)
	v_mfma_f32_32x32x16_bf16 v[2:17], v[186:189], v[214:217], v[2:17]
	ds_read_b128 v[186:189], v174 offset:29184
	v_max3_f32 v224, v224, v43, v44
	v_max3_f32 v225, v225, v59, v60
	v_max3_f32 v224, v224, v45, v46
	v_max3_f32 v225, v225, v61, v62
	s_waitcnt lgkmcnt(5)
	v_mfma_f32_32x32x16_bf16 v[18:33], v[190:193], v[214:217], v[18:33]
	ds_read_b128 v[190:193], v174 offset:22560
	v_max3_f32 v224, v224, v47, v48
	v_max3_f32 v225, v225, v63, v64
	v_max3_f32 v224, v224, v49, v65
	v_max_f32_e32 v224, v224, v225
	s_waitcnt lgkmcnt(4)
	v_mfma_f32_32x32x16_bf16 v[2:17], v[194:197], v[218:221], v[2:17]
	ds_read_b128 v[194:197], v174 offset:29216
	v_mov_b32_e32 v225, v224
	v_add_f32_e32 v1, v1, v164
	s_add_i32 s11, s11, 1
	v_permlane32_swap_b32_e32 v224, v225
	s_cmp_eq_u32 s9, s11
	v_max_f32_e32 v167, v224, v225
	v_cmp_lt_f32_e32 vcc, s66, v167
	s_waitcnt lgkmcnt(4)
	v_mfma_f32_32x32x16_bf16 v[18:33], v[198:201], v[218:221], v[18:33]
	s_waitcnt lgkmcnt(6)
	s_barrier
	s_branch .Lmla_p0
